# v8 + K-loop LDS-DMA in saddr form (SGPR base + 32-bit VGPR offset), 16 v_lshl_add_u64 per iteration removed
# speedup vs baseline: 1.0127x; 1.0127x over previous
; #define PG8_STAGE(bufoff, gbase, voff) do { _Pragma("unroll") for (int _i = 0; _i < 2; ++_i) \
;         __builtin_amdgcn_global_load_lds((const unsigned*)((const char*)(gbase) + (voff)[_i]), (PG8_LAS unsigned*)(lds + (bufoff) + ldsw + _i * 8192), 16, 0, 0); } while (0)
; #define PG8_LDA(dst, b, h) do { _Pragma("unroll") for (int m = 0; m < 4; ++m) _Pragma("unroll") for (int k = 0; k < 2; ++k) dst[m][k] = *(const PG8_LAS bf16x8*)(lds + PG8_SA(b, h) + aoff + m * 2048 + k * 1024); } while (0)
; #define PG8_LDB(dst, b, h) do { _Pragma("unroll") for (int n = 0; n < 2; ++n) _Pragma("unroll") for (int k = 0; k < 2; ++k) dst[n][k] = *(const PG8_LAS bf16x8*)(lds + PG8_SB(b, h) + boff + n * 2048 + k * 1024); } while (0)
; #define PG8_MMA(ai, bj, At, Bt) do { __builtin_amdgcn_s_setprio(1); _Pragma("unroll") for (int m = 0; m < 4; ++m) _Pragma("unroll") for (int n = 0; n < 2; ++n) _Pragma("unroll") for (int k = 0; k < 2; ++k) \
;         acc[ai][bj][m][n] = __builtin_amdgcn_mfma_f32_16x16x32_bf16(Bt[n][k], At[m][k], acc[ai][bj][m][n], 0, 0, 0); __builtin_amdgcn_s_setprio(0); } while (0)
; #define PG8_WAIT_V(n) asm volatile("s_waitcnt vmcnt(" #n ")" ::: "memory")
; #define PG8_WAIT_L(n) asm volatile("s_waitcnt lgkmcnt(" #n ")" ::: "memory")
; template <class Epi, class Sched, bool ALIGN_EPI = false, bool SP2 = false>
; __device__ __forceinline__ void gemm_phase(PG8_LAS unsigned char* lds, const Gemm g, const Sched& S, const Epi& E) {
;     ...
;             const bool last = (t == nt - 2);
;             const char* a1 = cA + (size_t)(t + 1) * kstep;
;             const char* a2 = last ? nA : cA + (size_t)(t + 2) * kstep; const char* b2 = last ? nB : cB + (size_t)(t + 2) * kstep;
;             const char* a3 = a2 + kstep; const char* b3 = b2 + kstep;
;             if (last && has_next) S.a_ready(nxt);
;             if constexpr (SP2) {
;             PG8_LDB(B0, 0, 0); PG8_LDB(B1, 0, 1); PG8_SCHED; PG8_LDA(At, 0, 0); PG8_STAGE(PG8_SA(1, 1), a1 + hA, voffA);
;             PG8_WAIT_V(8); PG8_WAIT_L(0); PG8_BAR; PG8_MMA(0, 0, At, B0); PG8_MMA(0, 1, At, B1); PG8_BAR; PG8_SCHED;
;             PG8_LDA(At, 0, 1); PG8_STAGE(PG8_SB(0, 0), b2, voffB); PG8_STAGE(PG8_SB(0, 1), b2 + hB, voffB); PG8_STAGE(PG8_SA(0, 0), a2, voffA);
;             PG8_WAIT_V(8); PG8_WAIT_L(0); PG8_BAR; PG8_MMA(1, 0, At, B0); PG8_MMA(1, 1, At, B1); PG8_BAR; PG8_SCHED;
.LBB0_190:
	ds_read_b128 v[130:133], v229
	ds_read_b128 v[134:137], v229 offset:1024
	ds_read_b128 v[138:141], v229 offset:2048
	ds_read_b128 v[142:145], v229 offset:3072
	ds_read_b128 v[146:149], v230
	ds_read_b128 v[150:153], v230 offset:1024
	ds_read_b128 v[154:157], v230 offset:2048
	ds_read_b128 v[158:161], v230 offset:3072
	s_add_u32 s64, s62, 0xfff80080
	s_addc_u32 s65, s63, -1
	s_cmp_eq_u32 s97, 28
	s_cselect_b32 s67, s11, s65
	s_cselect_b32 s66, s33, s64
	s_cselect_b32 s65, s53, s96
	s_cselect_b32 s64, s55, s61
	s_add_i32 m0, s74, 0xc000
	ds_read_b128 v[162:165], v231
	ds_read_b128 v[166:169], v231 offset:1024
	ds_read_b128 v[170:173], v231 offset:2048
	ds_read_b128 v[174:177], v231 offset:3072
	ds_read_b128 v[178:181], v231 offset:4096
	ds_read_b128 v[182:185], v231 offset:5120
	ds_read_b128 v[186:189], v231 offset:6144
	ds_read_b128 v[190:193], v231 offset:7168
	global_load_lds_dwordx4 v212, s[62:63]
	s_add_i32 m0, s74, 0xe000
	s_nop 0
	global_load_lds_dwordx4 v214, s[62:63]
	s_waitcnt vmcnt(8)
	s_waitcnt lgkmcnt(0)
	s_barrier
	s_waitcnt lgkmcnt(0)
	v_mfma_f32_16x16x32_bf16 v[126:129], v[130:133], v[162:165], v[126:129]
	v_mfma_f32_16x16x32_bf16 v[122:125], v[138:141], v[162:165], v[122:125]
	v_mfma_f32_16x16x32_bf16 v[110:113], v[130:133], v[170:173], v[110:113]
	v_mfma_f32_16x16x32_bf16 v[106:109], v[138:141], v[170:173], v[106:109]
	v_mfma_f32_16x16x32_bf16 v[94:97], v[130:133], v[178:181], v[94:97]
	v_mfma_f32_16x16x32_bf16 v[90:93], v[138:141], v[178:181], v[90:93]
	v_mfma_f32_16x16x32_bf16 v[78:81], v[130:133], v[186:189], v[78:81]
	v_mfma_f32_16x16x32_bf16 v[74:77], v[138:141], v[186:189], v[74:77]
	v_mfma_f32_16x16x32_bf16 v[126:129], v[134:137], v[166:169], v[126:129]
	v_mfma_f32_16x16x32_bf16 v[122:125], v[142:145], v[166:169], v[122:125]
	v_mfma_f32_16x16x32_bf16 v[110:113], v[134:137], v[174:177], v[110:113]
	v_mfma_f32_16x16x32_bf16 v[106:109], v[142:145], v[174:177], v[106:109]
	v_mfma_f32_16x16x32_bf16 v[94:97], v[134:137], v[182:185], v[94:97]
	v_mfma_f32_16x16x32_bf16 v[90:93], v[142:145], v[182:185], v[90:93]
	v_mfma_f32_16x16x32_bf16 v[78:81], v[134:137], v[190:193], v[78:81]
	v_mfma_f32_16x16x32_bf16 v[74:77], v[142:145], v[190:193], v[74:77]
	v_mfma_f32_16x16x32_bf16 v[118:121], v[146:149], v[162:165], v[118:121]
	v_mfma_f32_16x16x32_bf16 v[114:117], v[154:157], v[162:165], v[114:117]
	v_mfma_f32_16x16x32_bf16 v[102:105], v[146:149], v[170:173], v[102:105]
	v_mfma_f32_16x16x32_bf16 v[98:101], v[154:157], v[170:173], v[98:101]
	v_mfma_f32_16x16x32_bf16 v[86:89], v[146:149], v[178:181], v[86:89]
	v_mfma_f32_16x16x32_bf16 v[82:85], v[154:157], v[178:181], v[82:85]
	v_mfma_f32_16x16x32_bf16 v[70:73], v[146:149], v[186:189], v[70:73]
	v_mfma_f32_16x16x32_bf16 v[66:69], v[154:157], v[186:189], v[66:69]
	v_mfma_f32_16x16x32_bf16 v[118:121], v[150:153], v[166:169], v[118:121]
	v_mfma_f32_16x16x32_bf16 v[114:117], v[158:161], v[166:169], v[114:117]
	v_mfma_f32_16x16x32_bf16 v[102:105], v[150:153], v[174:177], v[102:105]
	v_mfma_f32_16x16x32_bf16 v[98:101], v[158:161], v[174:177], v[98:101]
	v_mfma_f32_16x16x32_bf16 v[86:89], v[150:153], v[182:185], v[86:89]
	v_mfma_f32_16x16x32_bf16 v[82:85], v[158:161], v[182:185], v[82:85]
	v_mfma_f32_16x16x32_bf16 v[70:73], v[150:153], v[190:193], v[70:73]
	v_mfma_f32_16x16x32_bf16 v[66:69], v[158:161], v[190:193], v[66:69]
	s_barrier
	s_add_i32 vcc_lo, s84, s73
	s_add_u32 s34, s64, s38
	s_addc_u32 s35, s65, s39
	s_mov_b32 m0, vcc_lo
	ds_read_b128 v[162:165], v231 offset:16384
	ds_read_b128 v[166:169], v231 offset:17408
	ds_read_b128 v[170:173], v231 offset:18432
	ds_read_b128 v[174:177], v231 offset:19456
	ds_read_b128 v[178:181], v231 offset:20480
	ds_read_b128 v[182:185], v231 offset:21504
	ds_read_b128 v[186:189], v231 offset:22528
	ds_read_b128 v[190:193], v231 offset:23552
	global_load_lds_dwordx4 v196, s[64:65]
	s_add_i32 m0, vcc_lo, 0x2000
	s_add_u32 vcc_lo, s64, 0x80000
	s_addc_u32 vcc_hi, s65, 0
	s_add_i32 s86, s85, s73
	global_load_lds_dwordx4 v200, s[64:65]
	s_mov_b32 m0, s86
	s_nop 0
	global_load_lds_dwordx4 v196, vcc
	s_add_i32 m0, s86, 0x2000
	s_nop 0
	global_load_lds_dwordx4 v200, vcc
	s_add_u32 s98, s66, s38
	s_addc_u32 s99, s67, s39
	s_mov_b32 m0, s74
	s_nop 0
	global_load_lds_dwordx4 v194, s[66:67]
	s_mov_b32 m0, s75
	s_nop 0
	global_load_lds_dwordx4 v198, s[66:67]
	s_waitcnt vmcnt(8)
	s_waitcnt lgkmcnt(0)
	s_barrier
	s_waitcnt lgkmcnt(0)
	v_mfma_f32_16x16x32_bf16 v[62:65], v[130:133], v[162:165], v[62:65]
	v_mfma_f32_16x16x32_bf16 v[58:61], v[138:141], v[162:165], v[58:61]
	v_mfma_f32_16x16x32_bf16 v[46:49], v[130:133], v[170:173], v[46:49]
	v_mfma_f32_16x16x32_bf16 v[42:45], v[138:141], v[170:173], v[42:45]
	v_mfma_f32_16x16x32_bf16 v[30:33], v[130:133], v[178:181], v[30:33]
	v_mfma_f32_16x16x32_bf16 v[26:29], v[138:141], v[178:181], v[26:29]
	v_mfma_f32_16x16x32_bf16 v[14:17], v[130:133], v[186:189], v[14:17]
	v_mfma_f32_16x16x32_bf16 v[10:13], v[138:141], v[186:189], v[10:13]
	v_mfma_f32_16x16x32_bf16 v[62:65], v[134:137], v[166:169], v[62:65]
	v_mfma_f32_16x16x32_bf16 v[58:61], v[142:145], v[166:169], v[58:61]
	v_mfma_f32_16x16x32_bf16 v[46:49], v[134:137], v[174:177], v[46:49]
	v_mfma_f32_16x16x32_bf16 v[42:45], v[142:145], v[174:177], v[42:45]
	v_mfma_f32_16x16x32_bf16 v[30:33], v[134:137], v[182:185], v[30:33]
	v_mfma_f32_16x16x32_bf16 v[26:29], v[142:145], v[182:185], v[26:29]
	v_mfma_f32_16x16x32_bf16 v[14:17], v[134:137], v[190:193], v[14:17]
	v_mfma_f32_16x16x32_bf16 v[10:13], v[142:145], v[190:193], v[10:13]
	v_mfma_f32_16x16x32_bf16 v[54:57], v[146:149], v[162:165], v[54:57]
	v_mfma_f32_16x16x32_bf16 v[50:53], v[154:157], v[162:165], v[50:53]
	v_mfma_f32_16x16x32_bf16 v[38:41], v[146:149], v[170:173], v[38:41]
	v_mfma_f32_16x16x32_bf16 v[34:37], v[154:157], v[170:173], v[34:37]
	v_mfma_f32_16x16x32_bf16 v[22:25], v[146:149], v[178:181], v[22:25]
	v_mfma_f32_16x16x32_bf16 v[18:21], v[154:157], v[178:181], v[18:21]
	v_mfma_f32_16x16x32_bf16 v[6:9], v[146:149], v[186:189], v[6:9]
	v_mfma_f32_16x16x32_bf16 v[2:5], v[154:157], v[186:189], v[2:5]
	v_mfma_f32_16x16x32_bf16 v[54:57], v[150:153], v[166:169], v[54:57]
	v_mfma_f32_16x16x32_bf16 v[50:53], v[158:161], v[166:169], v[50:53]
	v_mfma_f32_16x16x32_bf16 v[38:41], v[150:153], v[174:177], v[38:41]
	v_mfma_f32_16x16x32_bf16 v[34:37], v[158:161], v[174:177], v[34:37]
	v_mfma_f32_16x16x32_bf16 v[22:25], v[150:153], v[182:185], v[22:25]
	v_mfma_f32_16x16x32_bf16 v[18:21], v[158:161], v[182:185], v[18:21]
	v_mfma_f32_16x16x32_bf16 v[6:9], v[150:153], v[190:193], v[6:9]
	v_mfma_f32_16x16x32_bf16 v[2:5], v[158:161], v[190:193], v[2:5]
	s_barrier
; #define PG8_STAGE(bufoff, gbase, voff) do { _Pragma("unroll") for (int _i = 0; _i < 2; ++_i) \
;         __builtin_amdgcn_global_load_lds((const unsigned*)((const char*)(gbase) + (voff)[_i]), (PG8_LAS unsigned*)(lds + (bufoff) + ldsw + _i * 8192), 16, 0, 0); } while (0)
; #define PG8_LDA(dst, b, h) do { _Pragma("unroll") for (int m = 0; m < 4; ++m) _Pragma("unroll") for (int k = 0; k < 2; ++k) dst[m][k] = *(const PG8_LAS bf16x8*)(lds + PG8_SA(b, h) + aoff + m * 2048 + k * 1024); } while (0)
; #define PG8_LDB(dst, b, h) do { _Pragma("unroll") for (int n = 0; n < 2; ++n) _Pragma("unroll") for (int k = 0; k < 2; ++k) dst[n][k] = *(const PG8_LAS bf16x8*)(lds + PG8_SB(b, h) + boff + n * 2048 + k * 1024); } while (0)
; #define PG8_MMA(ai, bj, At, Bt) do { __builtin_amdgcn_s_setprio(1); _Pragma("unroll") for (int m = 0; m < 4; ++m) _Pragma("unroll") for (int n = 0; n < 2; ++n) _Pragma("unroll") for (int k = 0; k < 2; ++k) \
;         acc[ai][bj][m][n] = __builtin_amdgcn_mfma_f32_16x16x32_bf16(Bt[n][k], At[m][k], acc[ai][bj][m][n], 0, 0, 0); __builtin_amdgcn_s_setprio(0); } while (0)
; #define PG8_WAIT_V(n) asm volatile("s_waitcnt vmcnt(" #n ")" ::: "memory")
; #define PG8_WAIT_L(n) asm volatile("s_waitcnt lgkmcnt(" #n ")" ::: "memory")
; #define PG8_BAR __builtin_amdgcn_s_barrier()
; #define PG8_SCHED __builtin_amdgcn_sched_barrier(0)
; template <class Epi, class Sched, bool ALIGN_EPI = false, bool SP2 = false>
; __device__ __forceinline__ void gemm_phase(PG8_LAS unsigned char* lds, const Gemm g, const Sched& S, const Epi& E) {
;     ...
;             PG8_LDB(B0, 1, 0); PG8_LDB(B1, 1, 1); PG8_SCHED; PG8_LDA(At, 1, 0); PG8_STAGE(PG8_SA(0, 1), a2 + hA, voffA);
;             PG8_WAIT_V(8); PG8_WAIT_L(0); PG8_BAR; PG8_MMA(0, 0, At, B0); PG8_MMA(0, 1, At, B1); PG8_BAR; PG8_SCHED;
;             PG8_LDA(At, 1, 1); PG8_STAGE(PG8_SB(1, 0), b3, voffB); PG8_STAGE(PG8_SB(1, 1), b3 + hB, voffB); PG8_STAGE(PG8_SA(1, 0), a3, voffA);
;             PG8_WAIT_V(8); PG8_WAIT_L(0); PG8_BAR; PG8_MMA(1, 0, At, B0); PG8_MMA(1, 1, At, B1); PG8_BAR; PG8_SCHED;
;     __device__ __forceinline__ void operator()(AccRef acc, const pg8::Unit& u, int wr, int wc, int fr, int fq) const {
;         const int pn = u.pn, row0 = u.pm * 256 + wr * 64 + fr, cl = wc * 32 + 8 * fq;
;         if (pn < 16) {
	s_add_i32 s86, 0, 0x18000
	s_add_i32 vcc_lo, 0, 0x1c000
	v_add_u32_e32 v142, s86, v223
	v_add_u32_e32 v158, vcc_lo, v223
	ds_read_b128 v[130:133], v142
	ds_read_b128 v[134:137], v142 offset:1024
	ds_read_b128 v[138:141], v142 offset:2048
	ds_read_b128 v[142:145], v142 offset:3072
	ds_read_b128 v[146:149], v158
	ds_read_b128 v[150:153], v158 offset:1024
	ds_read_b128 v[154:157], v158 offset:2048
	ds_read_b128 v[158:161], v158 offset:3072
	s_add_u32 s66, s66, 0x80000
	s_addc_u32 s67, s67, 0
	s_mov_b32 m0, s76
	ds_read_b128 v[162:165], v231 offset:32768
	ds_read_b128 v[166:169], v231 offset:33792
	ds_read_b128 v[170:173], v231 offset:34816
	ds_read_b128 v[174:177], v231 offset:35840
	ds_read_b128 v[178:181], v231 offset:36864
	ds_read_b128 v[182:185], v231 offset:37888
	ds_read_b128 v[186:189], v231 offset:38912
	ds_read_b128 v[190:193], v231 offset:39936
	global_load_lds_dwordx4 v194, s[66:67]
	s_mov_b32 m0, s77
	s_nop 0
	global_load_lds_dwordx4 v198, s[66:67]
	s_waitcnt vmcnt(8)
	s_waitcnt lgkmcnt(0)
	s_barrier
	s_waitcnt lgkmcnt(0)
	v_mfma_f32_16x16x32_bf16 v[126:129], v[130:133], v[162:165], v[126:129]
	v_mfma_f32_16x16x32_bf16 v[122:125], v[138:141], v[162:165], v[122:125]
	v_mfma_f32_16x16x32_bf16 v[110:113], v[130:133], v[170:173], v[110:113]
	v_mfma_f32_16x16x32_bf16 v[106:109], v[138:141], v[170:173], v[106:109]
	v_mfma_f32_16x16x32_bf16 v[94:97], v[130:133], v[178:181], v[94:97]
	v_mfma_f32_16x16x32_bf16 v[90:93], v[138:141], v[178:181], v[90:93]
	v_mfma_f32_16x16x32_bf16 v[78:81], v[130:133], v[186:189], v[78:81]
	v_mfma_f32_16x16x32_bf16 v[74:77], v[138:141], v[186:189], v[74:77]
	v_mfma_f32_16x16x32_bf16 v[126:129], v[134:137], v[166:169], v[126:129]
	v_mfma_f32_16x16x32_bf16 v[122:125], v[142:145], v[166:169], v[122:125]
	v_mfma_f32_16x16x32_bf16 v[110:113], v[134:137], v[174:177], v[110:113]
	v_mfma_f32_16x16x32_bf16 v[106:109], v[142:145], v[174:177], v[106:109]
	v_mfma_f32_16x16x32_bf16 v[94:97], v[134:137], v[182:185], v[94:97]
	v_mfma_f32_16x16x32_bf16 v[90:93], v[142:145], v[182:185], v[90:93]
	v_mfma_f32_16x16x32_bf16 v[78:81], v[134:137], v[190:193], v[78:81]
	v_mfma_f32_16x16x32_bf16 v[74:77], v[142:145], v[190:193], v[74:77]
	v_mfma_f32_16x16x32_bf16 v[118:121], v[146:149], v[162:165], v[118:121]
	v_mfma_f32_16x16x32_bf16 v[114:117], v[154:157], v[162:165], v[114:117]
	v_mfma_f32_16x16x32_bf16 v[102:105], v[146:149], v[170:173], v[102:105]
	v_mfma_f32_16x16x32_bf16 v[98:101], v[154:157], v[170:173], v[98:101]
	v_mfma_f32_16x16x32_bf16 v[86:89], v[146:149], v[178:181], v[86:89]
	v_mfma_f32_16x16x32_bf16 v[82:85], v[154:157], v[178:181], v[82:85]
	v_mfma_f32_16x16x32_bf16 v[70:73], v[146:149], v[186:189], v[70:73]
	v_mfma_f32_16x16x32_bf16 v[66:69], v[154:157], v[186:189], v[66:69]
	v_mfma_f32_16x16x32_bf16 v[118:121], v[150:153], v[166:169], v[118:121]
	v_mfma_f32_16x16x32_bf16 v[114:117], v[158:161], v[166:169], v[114:117]
	v_mfma_f32_16x16x32_bf16 v[102:105], v[150:153], v[174:177], v[102:105]
	v_mfma_f32_16x16x32_bf16 v[98:101], v[158:161], v[174:177], v[98:101]
	v_mfma_f32_16x16x32_bf16 v[86:89], v[150:153], v[182:185], v[86:89]
	v_mfma_f32_16x16x32_bf16 v[82:85], v[158:161], v[182:185], v[82:85]
	v_mfma_f32_16x16x32_bf16 v[70:73], v[150:153], v[190:193], v[70:73]
	v_mfma_f32_16x16x32_bf16 v[66:69], v[158:161], v[190:193], v[66:69]
	s_barrier
	s_add_i32 s66, s86, s73
	s_mov_b32 m0, s66
	ds_read_b128 v[162:165], v231 offset:49152
	ds_read_b128 v[166:169], v231 offset:50176
	ds_read_b128 v[170:173], v231 offset:51200
	ds_read_b128 v[174:177], v231 offset:52224
	ds_read_b128 v[178:181], v231 offset:53248
	ds_read_b128 v[182:185], v231 offset:54272
	ds_read_b128 v[186:189], v231 offset:55296
	ds_read_b128 v[190:193], v231 offset:56320
	global_load_lds_dwordx4 v196, s[34:35]
	s_add_i32 m0, s66, 0x2000
	s_add_u32 s64, s64, 0x80080
	s_addc_u32 s65, s65, 0
	s_add_i32 s66, vcc_lo, s73
	global_load_lds_dwordx4 v200, s[34:35]
	s_mov_b32 m0, s66
	s_nop 0
	global_load_lds_dwordx4 v196, s[64:65]
	s_add_i32 m0, s66, 0x2000
	s_nop 0
	global_load_lds_dwordx4 v200, s[64:65]
	s_mov_b32 m0, s81
	s_nop 0
	global_load_lds_dwordx4 v194, s[98:99]
	s_mov_b32 m0, s82
	s_nop 0
	global_load_lds_dwordx4 v198, s[98:99]
	s_waitcnt vmcnt(8)
	s_waitcnt lgkmcnt(0)
	s_barrier
	s_waitcnt lgkmcnt(0)
	v_mfma_f32_16x16x32_bf16 v[62:65], v[130:133], v[162:165], v[62:65]
	v_mfma_f32_16x16x32_bf16 v[58:61], v[138:141], v[162:165], v[58:61]
	v_mfma_f32_16x16x32_bf16 v[46:49], v[130:133], v[170:173], v[46:49]
	v_mfma_f32_16x16x32_bf16 v[42:45], v[138:141], v[170:173], v[42:45]
	v_mfma_f32_16x16x32_bf16 v[30:33], v[130:133], v[178:181], v[30:33]
	v_mfma_f32_16x16x32_bf16 v[26:29], v[138:141], v[178:181], v[26:29]
	v_mfma_f32_16x16x32_bf16 v[14:17], v[130:133], v[186:189], v[14:17]
	v_mfma_f32_16x16x32_bf16 v[10:13], v[138:141], v[186:189], v[10:13]
	v_mfma_f32_16x16x32_bf16 v[62:65], v[134:137], v[166:169], v[62:65]
	v_mfma_f32_16x16x32_bf16 v[58:61], v[142:145], v[166:169], v[58:61]
	v_mfma_f32_16x16x32_bf16 v[46:49], v[134:137], v[174:177], v[46:49]
	v_mfma_f32_16x16x32_bf16 v[42:45], v[142:145], v[174:177], v[42:45]
	v_mfma_f32_16x16x32_bf16 v[30:33], v[134:137], v[182:185], v[30:33]
	v_mfma_f32_16x16x32_bf16 v[26:29], v[142:145], v[182:185], v[26:29]
	v_mfma_f32_16x16x32_bf16 v[14:17], v[134:137], v[190:193], v[14:17]
	v_mfma_f32_16x16x32_bf16 v[10:13], v[142:145], v[190:193], v[10:13]
	v_mfma_f32_16x16x32_bf16 v[54:57], v[146:149], v[162:165], v[54:57]
	v_mfma_f32_16x16x32_bf16 v[50:53], v[154:157], v[162:165], v[50:53]
	v_mfma_f32_16x16x32_bf16 v[38:41], v[146:149], v[170:173], v[38:41]
	v_mfma_f32_16x16x32_bf16 v[34:37], v[154:157], v[170:173], v[34:37]
	v_mfma_f32_16x16x32_bf16 v[22:25], v[146:149], v[178:181], v[22:25]
	v_mfma_f32_16x16x32_bf16 v[18:21], v[154:157], v[178:181], v[18:21]
	v_mfma_f32_16x16x32_bf16 v[6:9], v[146:149], v[186:189], v[6:9]
	v_mfma_f32_16x16x32_bf16 v[2:5], v[154:157], v[186:189], v[2:5]
	v_mfma_f32_16x16x32_bf16 v[54:57], v[150:153], v[166:169], v[54:57]
	v_mfma_f32_16x16x32_bf16 v[50:53], v[158:161], v[166:169], v[50:53]
	v_mfma_f32_16x16x32_bf16 v[38:41], v[150:153], v[174:177], v[38:41]
	v_mfma_f32_16x16x32_bf16 v[34:37], v[158:161], v[174:177], v[34:37]
	v_mfma_f32_16x16x32_bf16 v[22:25], v[150:153], v[182:185], v[22:25]
	v_mfma_f32_16x16x32_bf16 v[18:21], v[158:161], v[182:185], v[18:21]
	v_mfma_f32_16x16x32_bf16 v[6:9], v[150:153], v[190:193], v[6:9]
	v_mfma_f32_16x16x32_bf16 v[2:5], v[158:161], v[190:193], v[2:5]
	s_barrier
	s_add_i32 s97, s97, 2
	s_add_u32 s62, s62, 0x100
	s_addc_u32 s63, s63, 0
	s_add_u32 s61, s61, 0x100
	s_addc_u32 s96, s96, 0
	s_cmp_gt_u32 s97, 29
	s_cbranch_scc0 .LBB0_190
	s_and_b64 vcc, exec, s[40:41]
	s_cbranch_vccz .LBB0_211
	s_barrier
	v_lshl_add_u32 v220, s60, 8, v1
	s_cmp_gt_i32 s10, 15
	s_mov_b64 s[60:61], -1
	s_cbranch_scc1 .LBB0_212

; #define PG8_STAGE(bufoff, gbase, voff) do { _Pragma("unroll") for (int _i = 0; _i < 2; ++_i) \
;         __builtin_amdgcn_global_load_lds((const unsigned*)((const char*)(gbase) + (voff)[_i]), (PG8_LAS unsigned*)(lds + (bufoff) + ldsw + _i * 8192), 16, 0, 0); } while (0)
; #define PG8_LDA(dst, b, h) do { _Pragma("unroll") for (int m = 0; m < 4; ++m) _Pragma("unroll") for (int k = 0; k < 2; ++k) dst[m][k] = *(const PG8_LAS bf16x8*)(lds + PG8_SA(b, h) + aoff + m * 2048 + k * 1024); } while (0)
; #define PG8_LDB(dst, b, h) do { _Pragma("unroll") for (int n = 0; n < 2; ++n) _Pragma("unroll") for (int k = 0; k < 2; ++k) dst[n][k] = *(const PG8_LAS bf16x8*)(lds + PG8_SB(b, h) + boff + n * 2048 + k * 1024); } while (0)
; #define PG8_MMA(ai, bj, At, Bt) do { __builtin_amdgcn_s_setprio(1); _Pragma("unroll") for (int m = 0; m < 4; ++m) _Pragma("unroll") for (int n = 0; n < 2; ++n) _Pragma("unroll") for (int k = 0; k < 2; ++k) \
;         acc[ai][bj][m][n] = __builtin_amdgcn_mfma_f32_16x16x32_bf16(Bt[n][k], At[m][k], acc[ai][bj][m][n], 0, 0, 0); __builtin_amdgcn_s_setprio(0); } while (0)
; #define PG8_WAIT_V(n) asm volatile("s_waitcnt vmcnt(" #n ")" ::: "memory")
; #define PG8_WAIT_L(n) asm volatile("s_waitcnt lgkmcnt(" #n ")" ::: "memory")
; #define PG8_BAR __builtin_amdgcn_s_barrier()
; #define PG8_SCHED __builtin_amdgcn_sched_barrier(0)
; template <class Epi, class Sched, bool ALIGN_EPI = false, bool SP2 = false>
; __device__ __forceinline__ void gemm_phase(PG8_LAS unsigned char* lds, const Gemm g, const Sched& S, const Epi& E) {
;     ...
;             PG8_LDB(B0, 0, 0); PG8_LDB(B1, 0, 1); PG8_SCHED; PG8_LDA(At, 0, 0); PG8_STAGE(PG8_SA(1, 1), a1 + hA, voffA);
;             PG8_WAIT_V(8); PG8_WAIT_L(0); PG8_BAR; PG8_MMA(0, 0, At, B0); PG8_MMA(0, 1, At, B1); PG8_BAR; PG8_SCHED;
;             PG8_LDA(At, 0, 1); PG8_STAGE(PG8_SB(0, 0), b2, voffB); PG8_STAGE(PG8_SB(0, 1), b2 + hB, voffB); PG8_STAGE(PG8_SA(0, 0), a2, voffA);
;             PG8_WAIT_V(8); PG8_WAIT_L(0); PG8_BAR; PG8_MMA(1, 0, At, B0); PG8_MMA(1, 1, At, B1); PG8_BAR; PG8_SCHED;
.LBB0_868:
	ds_read_b128 v[146:149], v156
	ds_read_b128 v[150:153], v156 offset:1024
	ds_read_b128 v[160:163], v156 offset:2048
	ds_read_b128 v[164:167], v156 offset:3072
	ds_read_b128 v[168:171], v157
	ds_read_b128 v[172:175], v157 offset:1024
	ds_read_b128 v[176:179], v157 offset:2048
	ds_read_b128 v[180:183], v157 offset:3072
	s_add_u32 s18, s42, 0xfffc0080
	s_addc_u32 s19, s43, -1
	s_cmp_eq_u32 s72, 12
	s_cselect_b32 s47, s23, s19
	s_cselect_b32 s46, s67, s18
	s_cselect_b32 s45, s21, s71
	s_cselect_b32 s44, s69, s70
	s_add_i32 m0, s41, 0xc000
	ds_read_b128 v[184:187], v158
	ds_read_b128 v[188:191], v158 offset:1024
	ds_read_b128 v[192:195], v158 offset:2048
	ds_read_b128 v[196:199], v158 offset:3072
	ds_read_b128 v[200:203], v158 offset:4096
	ds_read_b128 v[204:207], v158 offset:5120
	ds_read_b128 v[208:211], v158 offset:6144
	ds_read_b128 v[212:215], v158 offset:7168
	global_load_lds_dwordx4 v138, s[42:43]
	s_add_i32 m0, s41, 0xe000
	s_nop 0
	global_load_lds_dwordx4 v140, s[42:43]
	s_waitcnt vmcnt(8)
	s_waitcnt lgkmcnt(0)
	s_barrier
	s_waitcnt lgkmcnt(0)
	v_mfma_f32_16x16x32_bf16 v[126:129], v[146:149], v[184:187], v[126:129]
	v_mfma_f32_16x16x32_bf16 v[122:125], v[160:163], v[184:187], v[122:125]
	v_mfma_f32_16x16x32_bf16 v[114:117], v[146:149], v[192:195], v[114:117]
	v_mfma_f32_16x16x32_bf16 v[106:109], v[160:163], v[192:195], v[106:109]
	v_mfma_f32_16x16x32_bf16 v[98:101], v[146:149], v[200:203], v[98:101]
	v_mfma_f32_16x16x32_bf16 v[90:93], v[160:163], v[200:203], v[90:93]
	v_mfma_f32_16x16x32_bf16 v[82:85], v[146:149], v[208:211], v[82:85]
	v_mfma_f32_16x16x32_bf16 v[74:77], v[160:163], v[208:211], v[74:77]
	v_mfma_f32_16x16x32_bf16 v[126:129], v[150:153], v[188:191], v[126:129]
	v_mfma_f32_16x16x32_bf16 v[122:125], v[164:167], v[188:191], v[122:125]
	v_mfma_f32_16x16x32_bf16 v[114:117], v[150:153], v[196:199], v[114:117]
	v_mfma_f32_16x16x32_bf16 v[106:109], v[164:167], v[196:199], v[106:109]
	v_mfma_f32_16x16x32_bf16 v[98:101], v[150:153], v[204:207], v[98:101]
	v_mfma_f32_16x16x32_bf16 v[90:93], v[164:167], v[204:207], v[90:93]
	v_mfma_f32_16x16x32_bf16 v[82:85], v[150:153], v[212:215], v[82:85]
	v_mfma_f32_16x16x32_bf16 v[74:77], v[164:167], v[212:215], v[74:77]
	v_mfma_f32_16x16x32_bf16 v[118:121], v[168:171], v[184:187], v[118:121]
	v_mfma_f32_16x16x32_bf16 v[110:113], v[176:179], v[184:187], v[110:113]
	v_mfma_f32_16x16x32_bf16 v[102:105], v[168:171], v[192:195], v[102:105]
	v_mfma_f32_16x16x32_bf16 v[94:97], v[176:179], v[192:195], v[94:97]
	v_mfma_f32_16x16x32_bf16 v[86:89], v[168:171], v[200:203], v[86:89]
	v_mfma_f32_16x16x32_bf16 v[78:81], v[176:179], v[200:203], v[78:81]
	v_mfma_f32_16x16x32_bf16 v[70:73], v[168:171], v[208:211], v[70:73]
	v_mfma_f32_16x16x32_bf16 v[66:69], v[176:179], v[208:211], v[66:69]
	v_mfma_f32_16x16x32_bf16 v[118:121], v[172:175], v[188:191], v[118:121]
	v_mfma_f32_16x16x32_bf16 v[110:113], v[180:183], v[188:191], v[110:113]
	v_mfma_f32_16x16x32_bf16 v[102:105], v[172:175], v[196:199], v[102:105]
	v_mfma_f32_16x16x32_bf16 v[94:97], v[180:183], v[196:199], v[94:97]
	v_mfma_f32_16x16x32_bf16 v[86:89], v[172:175], v[204:207], v[86:89]
	v_mfma_f32_16x16x32_bf16 v[78:81], v[180:183], v[204:207], v[78:81]
	v_mfma_f32_16x16x32_bf16 v[70:73], v[172:175], v[212:215], v[70:73]
	v_mfma_f32_16x16x32_bf16 v[66:69], v[180:183], v[212:215], v[66:69]
	s_barrier
	s_add_i32 s18, s64, s52
	s_add_u32 s78, s44, s8
	s_addc_u32 s79, s45, s9
	s_mov_b32 m0, s18
	ds_read_b128 v[184:187], v158 offset:16384
	ds_read_b128 v[188:191], v158 offset:17408
	ds_read_b128 v[192:195], v158 offset:18432
	ds_read_b128 v[196:199], v158 offset:19456
	ds_read_b128 v[200:203], v158 offset:20480
	ds_read_b128 v[204:207], v158 offset:21504
	ds_read_b128 v[208:211], v158 offset:22528
	ds_read_b128 v[212:215], v158 offset:23552
	global_load_lds_dwordx4 v134, s[44:45]
	s_add_i32 m0, s18, 0x2000
	s_add_u32 s74, s44, 0x40000
	s_addc_u32 s75, s45, 0
	s_add_i32 s18, s65, s52
	global_load_lds_dwordx4 v130, s[44:45]
	s_mov_b32 m0, s18
	s_nop 0
	global_load_lds_dwordx4 v134, s[74:75]
	s_add_i32 m0, s18, 0x2000
	s_nop 0
	global_load_lds_dwordx4 v130, s[74:75]
	s_add_u32 s80, s46, s8
	s_addc_u32 s81, s47, s9
	s_mov_b32 m0, s41
	s_nop 0
	global_load_lds_dwordx4 v136, s[46:47]
	s_mov_b32 m0, s53
	s_nop 0
	global_load_lds_dwordx4 v132, s[46:47]
	s_waitcnt vmcnt(8)
	s_waitcnt lgkmcnt(0)
	s_barrier
	s_waitcnt lgkmcnt(0)
	v_mfma_f32_16x16x32_bf16 v[62:65], v[146:149], v[184:187], v[62:65]
	v_mfma_f32_16x16x32_bf16 v[58:61], v[160:163], v[184:187], v[58:61]
	v_mfma_f32_16x16x32_bf16 v[50:53], v[146:149], v[192:195], v[50:53]
	v_mfma_f32_16x16x32_bf16 v[42:45], v[160:163], v[192:195], v[42:45]
	v_mfma_f32_16x16x32_bf16 v[34:37], v[146:149], v[200:203], v[34:37]
	v_mfma_f32_16x16x32_bf16 v[26:29], v[160:163], v[200:203], v[26:29]
	v_mfma_f32_16x16x32_bf16 v[18:21], v[146:149], v[208:211], v[18:21]
	v_mfma_f32_16x16x32_bf16 v[10:13], v[160:163], v[208:211], v[10:13]
	v_mfma_f32_16x16x32_bf16 v[62:65], v[150:153], v[188:191], v[62:65]
	v_mfma_f32_16x16x32_bf16 v[58:61], v[164:167], v[188:191], v[58:61]
	v_mfma_f32_16x16x32_bf16 v[50:53], v[150:153], v[196:199], v[50:53]
	v_mfma_f32_16x16x32_bf16 v[42:45], v[164:167], v[196:199], v[42:45]
	v_mfma_f32_16x16x32_bf16 v[34:37], v[150:153], v[204:207], v[34:37]
	v_mfma_f32_16x16x32_bf16 v[26:29], v[164:167], v[204:207], v[26:29]
	v_mfma_f32_16x16x32_bf16 v[18:21], v[150:153], v[212:215], v[18:21]
	v_mfma_f32_16x16x32_bf16 v[10:13], v[164:167], v[212:215], v[10:13]
	v_mfma_f32_16x16x32_bf16 v[54:57], v[168:171], v[184:187], v[54:57]
	v_mfma_f32_16x16x32_bf16 v[46:49], v[176:179], v[184:187], v[46:49]
	v_mfma_f32_16x16x32_bf16 v[38:41], v[168:171], v[192:195], v[38:41]
	v_mfma_f32_16x16x32_bf16 v[30:33], v[176:179], v[192:195], v[30:33]
	v_mfma_f32_16x16x32_bf16 v[22:25], v[168:171], v[200:203], v[22:25]
	v_mfma_f32_16x16x32_bf16 v[14:17], v[176:179], v[200:203], v[14:17]
	v_mfma_f32_16x16x32_bf16 v[6:9], v[168:171], v[208:211], v[6:9]
	v_mfma_f32_16x16x32_bf16 v[2:5], v[176:179], v[208:211], v[2:5]
	v_mfma_f32_16x16x32_bf16 v[54:57], v[172:175], v[188:191], v[54:57]
	v_mfma_f32_16x16x32_bf16 v[46:49], v[180:183], v[188:191], v[46:49]
	v_mfma_f32_16x16x32_bf16 v[38:41], v[172:175], v[196:199], v[38:41]
	v_mfma_f32_16x16x32_bf16 v[30:33], v[180:183], v[196:199], v[30:33]
	v_mfma_f32_16x16x32_bf16 v[22:25], v[172:175], v[204:207], v[22:25]
	v_mfma_f32_16x16x32_bf16 v[14:17], v[180:183], v[204:207], v[14:17]
	v_mfma_f32_16x16x32_bf16 v[6:9], v[172:175], v[212:215], v[6:9]
	v_mfma_f32_16x16x32_bf16 v[2:5], v[180:183], v[212:215], v[2:5]
	s_barrier
; #define PG8_STAGE(bufoff, gbase, voff) do { _Pragma("unroll") for (int _i = 0; _i < 2; ++_i) \
;         __builtin_amdgcn_global_load_lds((const unsigned*)((const char*)(gbase) + (voff)[_i]), (PG8_LAS unsigned*)(lds + (bufoff) + ldsw + _i * 8192), 16, 0, 0); } while (0)
; #define PG8_LDA(dst, b, h) do { _Pragma("unroll") for (int m = 0; m < 4; ++m) _Pragma("unroll") for (int k = 0; k < 2; ++k) dst[m][k] = *(const PG8_LAS bf16x8*)(lds + PG8_SA(b, h) + aoff + m * 2048 + k * 1024); } while (0)
; #define PG8_LDB(dst, b, h) do { _Pragma("unroll") for (int n = 0; n < 2; ++n) _Pragma("unroll") for (int k = 0; k < 2; ++k) dst[n][k] = *(const PG8_LAS bf16x8*)(lds + PG8_SB(b, h) + boff + n * 2048 + k * 1024); } while (0)
; #define PG8_MMA(ai, bj, At, Bt) do { __builtin_amdgcn_s_setprio(1); _Pragma("unroll") for (int m = 0; m < 4; ++m) _Pragma("unroll") for (int n = 0; n < 2; ++n) _Pragma("unroll") for (int k = 0; k < 2; ++k) \
;         acc[ai][bj][m][n] = __builtin_amdgcn_mfma_f32_16x16x32_bf16(Bt[n][k], At[m][k], acc[ai][bj][m][n], 0, 0, 0); __builtin_amdgcn_s_setprio(0); } while (0)
; #define PG8_WAIT_V(n) asm volatile("s_waitcnt vmcnt(" #n ")" ::: "memory")
; #define PG8_WAIT_L(n) asm volatile("s_waitcnt lgkmcnt(" #n ")" ::: "memory")
; #define PG8_BAR __builtin_amdgcn_s_barrier()
; #define PG8_SCHED __builtin_amdgcn_sched_barrier(0)
; template <class Epi, class Sched, bool ALIGN_EPI = false, bool SP2 = false>
; __device__ __forceinline__ void gemm_phase(PG8_LAS unsigned char* lds, const Gemm g, const Sched& S, const Epi& E) {
;     ...
;             PG8_LDB(B0, 1, 0); PG8_LDB(B1, 1, 1); PG8_SCHED; PG8_LDA(At, 1, 0); PG8_STAGE(PG8_SA(0, 1), a2 + hA, voffA);
;             PG8_WAIT_V(8); PG8_WAIT_L(0); PG8_BAR; PG8_MMA(0, 0, At, B0); PG8_MMA(0, 1, At, B1); PG8_BAR; PG8_SCHED;
;             PG8_LDA(At, 1, 1); PG8_STAGE(PG8_SB(1, 0), b3, voffB); PG8_STAGE(PG8_SB(1, 1), b3 + hB, voffB); PG8_STAGE(PG8_SA(1, 0), a3, voffA);
;             PG8_WAIT_V(8); PG8_WAIT_L(0); PG8_BAR; PG8_MMA(1, 0, At, B0); PG8_MMA(1, 1, At, B1); PG8_BAR; PG8_SCHED;
	s_add_i32 s18, 0, 0x18000
	v_add_u32_e32 v159, s18, v154
	s_add_i32 s19, 0, 0x1c000
	ds_read_b128 v[146:149], v159
	ds_read_b128 v[150:153], v159 offset:1024
	ds_read_b128 v[160:163], v159 offset:2048
	ds_read_b128 v[164:167], v159 offset:3072
	v_add_u32_e32 v159, s19, v154
	ds_read_b128 v[168:171], v159
	ds_read_b128 v[172:175], v159 offset:1024
	ds_read_b128 v[176:179], v159 offset:2048
	ds_read_b128 v[180:183], v159 offset:3072
	s_add_u32 s46, s46, 0x40000
	s_addc_u32 s47, s47, 0
	s_mov_b32 m0, s58
	ds_read_b128 v[184:187], v158 offset:32768
	ds_read_b128 v[188:191], v158 offset:33792
	ds_read_b128 v[192:195], v158 offset:34816
	ds_read_b128 v[196:199], v158 offset:35840
	ds_read_b128 v[200:203], v158 offset:36864
	ds_read_b128 v[204:207], v158 offset:37888
	ds_read_b128 v[208:211], v158 offset:38912
	ds_read_b128 v[212:215], v158 offset:39936
	global_load_lds_dwordx4 v136, s[46:47]
	s_mov_b32 m0, s59
	s_nop 0
	global_load_lds_dwordx4 v132, s[46:47]
	s_waitcnt vmcnt(8)
	s_waitcnt lgkmcnt(0)
	s_barrier
	s_waitcnt lgkmcnt(0)
	v_mfma_f32_16x16x32_bf16 v[126:129], v[146:149], v[184:187], v[126:129]
	v_mfma_f32_16x16x32_bf16 v[122:125], v[160:163], v[184:187], v[122:125]
	v_mfma_f32_16x16x32_bf16 v[114:117], v[146:149], v[192:195], v[114:117]
	v_mfma_f32_16x16x32_bf16 v[106:109], v[160:163], v[192:195], v[106:109]
	v_mfma_f32_16x16x32_bf16 v[98:101], v[146:149], v[200:203], v[98:101]
	v_mfma_f32_16x16x32_bf16 v[90:93], v[160:163], v[200:203], v[90:93]
	v_mfma_f32_16x16x32_bf16 v[82:85], v[146:149], v[208:211], v[82:85]
	v_mfma_f32_16x16x32_bf16 v[74:77], v[160:163], v[208:211], v[74:77]
	v_mfma_f32_16x16x32_bf16 v[126:129], v[150:153], v[188:191], v[126:129]
	v_mfma_f32_16x16x32_bf16 v[122:125], v[164:167], v[188:191], v[122:125]
	v_mfma_f32_16x16x32_bf16 v[114:117], v[150:153], v[196:199], v[114:117]
	v_mfma_f32_16x16x32_bf16 v[106:109], v[164:167], v[196:199], v[106:109]
	v_mfma_f32_16x16x32_bf16 v[98:101], v[150:153], v[204:207], v[98:101]
	v_mfma_f32_16x16x32_bf16 v[90:93], v[164:167], v[204:207], v[90:93]
	v_mfma_f32_16x16x32_bf16 v[82:85], v[150:153], v[212:215], v[82:85]
	v_mfma_f32_16x16x32_bf16 v[74:77], v[164:167], v[212:215], v[74:77]
	v_mfma_f32_16x16x32_bf16 v[118:121], v[168:171], v[184:187], v[118:121]
	v_mfma_f32_16x16x32_bf16 v[110:113], v[176:179], v[184:187], v[110:113]
	v_mfma_f32_16x16x32_bf16 v[102:105], v[168:171], v[192:195], v[102:105]
	v_mfma_f32_16x16x32_bf16 v[94:97], v[176:179], v[192:195], v[94:97]
	v_mfma_f32_16x16x32_bf16 v[86:89], v[168:171], v[200:203], v[86:89]
	v_mfma_f32_16x16x32_bf16 v[78:81], v[176:179], v[200:203], v[78:81]
	v_mfma_f32_16x16x32_bf16 v[70:73], v[168:171], v[208:211], v[70:73]
	v_mfma_f32_16x16x32_bf16 v[66:69], v[176:179], v[208:211], v[66:69]
	v_mfma_f32_16x16x32_bf16 v[118:121], v[172:175], v[188:191], v[118:121]
	v_mfma_f32_16x16x32_bf16 v[110:113], v[180:183], v[188:191], v[110:113]
	v_mfma_f32_16x16x32_bf16 v[102:105], v[172:175], v[196:199], v[102:105]
	v_mfma_f32_16x16x32_bf16 v[94:97], v[180:183], v[196:199], v[94:97]
	v_mfma_f32_16x16x32_bf16 v[86:89], v[172:175], v[204:207], v[86:89]
	v_mfma_f32_16x16x32_bf16 v[78:81], v[180:183], v[204:207], v[78:81]
	v_mfma_f32_16x16x32_bf16 v[70:73], v[172:175], v[212:215], v[70:73]
	v_mfma_f32_16x16x32_bf16 v[66:69], v[180:183], v[212:215], v[66:69]
	s_barrier
	s_add_i32 s18, s18, s52
	s_mov_b32 m0, s18
	ds_read_b128 v[184:187], v158 offset:49152
	ds_read_b128 v[188:191], v158 offset:50176
	ds_read_b128 v[192:195], v158 offset:51200
	ds_read_b128 v[196:199], v158 offset:52224
	ds_read_b128 v[200:203], v158 offset:53248
	ds_read_b128 v[204:207], v158 offset:54272
	ds_read_b128 v[208:211], v158 offset:55296
	ds_read_b128 v[212:215], v158 offset:56320
	global_load_lds_dwordx4 v134, s[78:79]
	s_add_i32 m0, s18, 0x2000
	s_add_u32 s44, s44, 0x40080
	s_addc_u32 s45, s45, 0
	s_add_i32 s18, s19, s52
	global_load_lds_dwordx4 v130, s[78:79]
	s_mov_b32 m0, s18
	s_nop 0
	global_load_lds_dwordx4 v134, s[44:45]
	s_add_i32 m0, s18, 0x2000
	s_nop 0
	global_load_lds_dwordx4 v130, s[44:45]
	s_mov_b32 m0, s60
	s_nop 0
	global_load_lds_dwordx4 v136, s[80:81]
	s_mov_b32 m0, s61
	s_nop 0
	global_load_lds_dwordx4 v132, s[80:81]
	s_waitcnt vmcnt(8)
	s_waitcnt lgkmcnt(0)
	s_barrier
	s_waitcnt lgkmcnt(0)
	v_mfma_f32_16x16x32_bf16 v[62:65], v[146:149], v[184:187], v[62:65]
	v_mfma_f32_16x16x32_bf16 v[58:61], v[160:163], v[184:187], v[58:61]
	v_mfma_f32_16x16x32_bf16 v[50:53], v[146:149], v[192:195], v[50:53]
	v_mfma_f32_16x16x32_bf16 v[42:45], v[160:163], v[192:195], v[42:45]
	v_mfma_f32_16x16x32_bf16 v[34:37], v[146:149], v[200:203], v[34:37]
	v_mfma_f32_16x16x32_bf16 v[26:29], v[160:163], v[200:203], v[26:29]
	v_mfma_f32_16x16x32_bf16 v[18:21], v[146:149], v[208:211], v[18:21]
	v_mfma_f32_16x16x32_bf16 v[10:13], v[160:163], v[208:211], v[10:13]
	v_mfma_f32_16x16x32_bf16 v[62:65], v[150:153], v[188:191], v[62:65]
	v_mfma_f32_16x16x32_bf16 v[58:61], v[164:167], v[188:191], v[58:61]
	v_mfma_f32_16x16x32_bf16 v[50:53], v[150:153], v[196:199], v[50:53]
	v_mfma_f32_16x16x32_bf16 v[42:45], v[164:167], v[196:199], v[42:45]
	v_mfma_f32_16x16x32_bf16 v[34:37], v[150:153], v[204:207], v[34:37]
	v_mfma_f32_16x16x32_bf16 v[26:29], v[164:167], v[204:207], v[26:29]
	v_mfma_f32_16x16x32_bf16 v[18:21], v[150:153], v[212:215], v[18:21]
	v_mfma_f32_16x16x32_bf16 v[10:13], v[164:167], v[212:215], v[10:13]
	v_mfma_f32_16x16x32_bf16 v[54:57], v[168:171], v[184:187], v[54:57]
	v_mfma_f32_16x16x32_bf16 v[46:49], v[176:179], v[184:187], v[46:49]
	v_mfma_f32_16x16x32_bf16 v[38:41], v[168:171], v[192:195], v[38:41]
	v_mfma_f32_16x16x32_bf16 v[30:33], v[176:179], v[192:195], v[30:33]
	v_mfma_f32_16x16x32_bf16 v[22:25], v[168:171], v[200:203], v[22:25]
	v_mfma_f32_16x16x32_bf16 v[14:17], v[176:179], v[200:203], v[14:17]
	v_mfma_f32_16x16x32_bf16 v[6:9], v[168:171], v[208:211], v[6:9]
	v_mfma_f32_16x16x32_bf16 v[2:5], v[176:179], v[208:211], v[2:5]
	v_mfma_f32_16x16x32_bf16 v[54:57], v[172:175], v[188:191], v[54:57]
	v_mfma_f32_16x16x32_bf16 v[46:49], v[180:183], v[188:191], v[46:49]
	v_mfma_f32_16x16x32_bf16 v[38:41], v[172:175], v[196:199], v[38:41]
	v_mfma_f32_16x16x32_bf16 v[30:33], v[180:183], v[196:199], v[30:33]
	v_mfma_f32_16x16x32_bf16 v[22:25], v[172:175], v[204:207], v[22:25]
	v_mfma_f32_16x16x32_bf16 v[14:17], v[180:183], v[204:207], v[14:17]
	v_mfma_f32_16x16x32_bf16 v[6:9], v[172:175], v[212:215], v[6:9]
	v_mfma_f32_16x16x32_bf16 v[2:5], v[180:183], v[212:215], v[2:5]
	s_barrier
	s_add_i32 s72, s72, 2
	s_add_u32 s42, s42, 0x100
	s_addc_u32 s43, s43, 0
	s_add_u32 s70, s70, 0x100
	s_addc_u32 s71, s71, 0
	s_cmp_gt_u32 s72, 13
	s_cbranch_scc0 .LBB0_868
	s_and_b64 vcc, exec, s[14:15]
	s_cbranch_vccz .LBB0_871
	s_barrier

; #define PG8_STAGE(bufoff, gbase, voff) do { _Pragma("unroll") for (int _i = 0; _i < 2; ++_i) \
;         __builtin_amdgcn_global_load_lds((const unsigned*)((const char*)(gbase) + (voff)[_i]), (PG8_LAS unsigned*)(lds + (bufoff) + ldsw + _i * 8192), 16, 0, 0); } while (0)
; #define PG8_LDA(dst, b, h) do { _Pragma("unroll") for (int m = 0; m < 4; ++m) _Pragma("unroll") for (int k = 0; k < 2; ++k) dst[m][k] = *(const PG8_LAS bf16x8*)(lds + PG8_SA(b, h) + aoff + m * 2048 + k * 1024); } while (0)
; #define PG8_LDB(dst, b, h) do { _Pragma("unroll") for (int n = 0; n < 2; ++n) _Pragma("unroll") for (int k = 0; k < 2; ++k) dst[n][k] = *(const PG8_LAS bf16x8*)(lds + PG8_SB(b, h) + boff + n * 2048 + k * 1024); } while (0)
; #define PG8_MMA(ai, bj, At, Bt) do { __builtin_amdgcn_s_setprio(1); _Pragma("unroll") for (int m = 0; m < 4; ++m) _Pragma("unroll") for (int n = 0; n < 2; ++n) _Pragma("unroll") for (int k = 0; k < 2; ++k) \
;         acc[ai][bj][m][n] = __builtin_amdgcn_mfma_f32_16x16x32_bf16(Bt[n][k], At[m][k], acc[ai][bj][m][n], 0, 0, 0); __builtin_amdgcn_s_setprio(0); } while (0)
; #define PG8_WAIT_V(n) asm volatile("s_waitcnt vmcnt(" #n ")" ::: "memory")
; #define PG8_WAIT_L(n) asm volatile("s_waitcnt lgkmcnt(" #n ")" ::: "memory")
; #define PG8_BAR __builtin_amdgcn_s_barrier()
; #define PG8_SCHED __builtin_amdgcn_sched_barrier(0)
; template <class Epi, class Sched, bool ALIGN_EPI = false, bool SP2 = false>
; __device__ __forceinline__ void gemm_phase(PG8_LAS unsigned char* lds, const Gemm g, const Sched& S, const Epi& E) {
;     ...
;             PG8_LDB(B0, 0, 0); PG8_LDB(B1, 0, 1); PG8_SCHED; PG8_LDA(At, 0, 0); PG8_STAGE(PG8_SA(1, 1), a1 + hA, voffA);
;             PG8_WAIT_V(8); PG8_WAIT_L(0); PG8_BAR; PG8_MMA(0, 0, At, B0); PG8_MMA(0, 1, At, B1); PG8_BAR; PG8_SCHED;
;             PG8_LDA(At, 0, 1); PG8_STAGE(PG8_SB(0, 0), b2, voffB); PG8_STAGE(PG8_SB(0, 1), b2 + hB, voffB); PG8_STAGE(PG8_SA(0, 0), a2, voffA);
;             PG8_WAIT_V(8); PG8_WAIT_L(0); PG8_BAR; PG8_MMA(1, 0, At, B0); PG8_MMA(1, 1, At, B1); PG8_BAR; PG8_SCHED;
.LBB0_888:
	ds_read_b128 v[130:133], v172
	ds_read_b128 v[134:137], v172 offset:1024
	ds_read_b128 v[138:141], v172 offset:2048
	ds_read_b128 v[142:145], v172 offset:3072
	ds_read_b128 v[162:165], v173
	ds_read_b128 v[166:169], v173 offset:1024
	ds_read_b128 v[176:179], v173 offset:2048
	ds_read_b128 v[180:183], v173 offset:3072
	s_add_u32 s18, s44, 0xfff80080
	s_addc_u32 s19, s45, -1
	s_cmp_eq_u32 s74, 28
	s_cselect_b32 s49, s25, s19
	s_cselect_b32 s48, s70, s18
	s_cselect_b32 s47, s23, s73
	s_cselect_b32 s46, s71, s72
	s_add_i32 m0, s43, 0xc000
	ds_read_b128 v[184:187], v174
	ds_read_b128 v[188:191], v174 offset:1024
	ds_read_b128 v[192:195], v174 offset:2048
	ds_read_b128 v[196:199], v174 offset:3072
	ds_read_b128 v[200:203], v174 offset:4096
	ds_read_b128 v[204:207], v174 offset:5120
	ds_read_b128 v[208:211], v174 offset:6144
	ds_read_b128 v[212:215], v174 offset:7168
	global_load_lds_dwordx4 v154, s[44:45]
	s_add_i32 m0, s43, 0xe000
	s_nop 0
	global_load_lds_dwordx4 v156, s[44:45]
	s_waitcnt vmcnt(8)
	s_waitcnt lgkmcnt(0)
	s_barrier
	s_waitcnt lgkmcnt(0)
	v_mfma_f32_16x16x32_bf16 v[126:129], v[130:133], v[184:187], v[126:129]
	v_mfma_f32_16x16x32_bf16 v[122:125], v[138:141], v[184:187], v[122:125]
	v_mfma_f32_16x16x32_bf16 v[110:113], v[130:133], v[192:195], v[110:113]
	v_mfma_f32_16x16x32_bf16 v[106:109], v[138:141], v[192:195], v[106:109]
	v_mfma_f32_16x16x32_bf16 v[94:97], v[130:133], v[200:203], v[94:97]
	v_mfma_f32_16x16x32_bf16 v[90:93], v[138:141], v[200:203], v[90:93]
	v_mfma_f32_16x16x32_bf16 v[78:81], v[130:133], v[208:211], v[78:81]
	v_mfma_f32_16x16x32_bf16 v[74:77], v[138:141], v[208:211], v[74:77]
	v_mfma_f32_16x16x32_bf16 v[126:129], v[134:137], v[188:191], v[126:129]
	v_mfma_f32_16x16x32_bf16 v[122:125], v[142:145], v[188:191], v[122:125]
	v_mfma_f32_16x16x32_bf16 v[110:113], v[134:137], v[196:199], v[110:113]
	v_mfma_f32_16x16x32_bf16 v[106:109], v[142:145], v[196:199], v[106:109]
	v_mfma_f32_16x16x32_bf16 v[94:97], v[134:137], v[204:207], v[94:97]
	v_mfma_f32_16x16x32_bf16 v[90:93], v[142:145], v[204:207], v[90:93]
	v_mfma_f32_16x16x32_bf16 v[78:81], v[134:137], v[212:215], v[78:81]
	v_mfma_f32_16x16x32_bf16 v[74:77], v[142:145], v[212:215], v[74:77]
	v_mfma_f32_16x16x32_bf16 v[118:121], v[162:165], v[184:187], v[118:121]
	v_mfma_f32_16x16x32_bf16 v[114:117], v[176:179], v[184:187], v[114:117]
	v_mfma_f32_16x16x32_bf16 v[102:105], v[162:165], v[192:195], v[102:105]
	v_mfma_f32_16x16x32_bf16 v[98:101], v[176:179], v[192:195], v[98:101]
	v_mfma_f32_16x16x32_bf16 v[86:89], v[162:165], v[200:203], v[86:89]
	v_mfma_f32_16x16x32_bf16 v[82:85], v[176:179], v[200:203], v[82:85]
	v_mfma_f32_16x16x32_bf16 v[70:73], v[162:165], v[208:211], v[70:73]
	v_mfma_f32_16x16x32_bf16 v[66:69], v[176:179], v[208:211], v[66:69]
	v_mfma_f32_16x16x32_bf16 v[118:121], v[166:169], v[188:191], v[118:121]
	v_mfma_f32_16x16x32_bf16 v[114:117], v[180:183], v[188:191], v[114:117]
	v_mfma_f32_16x16x32_bf16 v[102:105], v[166:169], v[196:199], v[102:105]
	v_mfma_f32_16x16x32_bf16 v[98:101], v[180:183], v[196:199], v[98:101]
	v_mfma_f32_16x16x32_bf16 v[86:89], v[166:169], v[204:207], v[86:89]
	v_mfma_f32_16x16x32_bf16 v[82:85], v[180:183], v[204:207], v[82:85]
	v_mfma_f32_16x16x32_bf16 v[70:73], v[166:169], v[212:215], v[70:73]
	v_mfma_f32_16x16x32_bf16 v[66:69], v[180:183], v[212:215], v[66:69]
	s_barrier
	s_add_i32 s18, s66, s58
	s_add_u32 s78, s46, s16
	s_addc_u32 s79, s47, s17
	s_mov_b32 m0, s18
	ds_read_b128 v[184:187], v174 offset:16384
	ds_read_b128 v[188:191], v174 offset:17408
	ds_read_b128 v[192:195], v174 offset:18432
	ds_read_b128 v[196:199], v174 offset:19456
	ds_read_b128 v[200:203], v174 offset:20480
	ds_read_b128 v[204:207], v174 offset:21504
	ds_read_b128 v[208:211], v174 offset:22528
	ds_read_b128 v[212:215], v174 offset:23552
	global_load_lds_dwordx4 v150, s[46:47]
	s_add_i32 m0, s18, 0x2000
	s_add_u32 s76, s46, 0x80000
	s_addc_u32 s77, s47, 0
	s_add_i32 s18, s67, s58
	global_load_lds_dwordx4 v146, s[46:47]
	s_mov_b32 m0, s18
	s_nop 0
	global_load_lds_dwordx4 v150, s[76:77]
	s_add_i32 m0, s18, 0x2000
	s_nop 0
	global_load_lds_dwordx4 v146, s[76:77]
	s_add_u32 s80, s48, s16
	s_addc_u32 s81, s49, s17
	s_mov_b32 m0, s43
	s_nop 0
	global_load_lds_dwordx4 v152, s[48:49]
	s_mov_b32 m0, s59
	s_nop 0
	global_load_lds_dwordx4 v148, s[48:49]
	s_waitcnt vmcnt(8)
	s_waitcnt lgkmcnt(0)
	s_barrier
	s_waitcnt lgkmcnt(0)
	v_mfma_f32_16x16x32_bf16 v[62:65], v[130:133], v[184:187], v[62:65]
	v_mfma_f32_16x16x32_bf16 v[58:61], v[138:141], v[184:187], v[58:61]
	v_mfma_f32_16x16x32_bf16 v[46:49], v[130:133], v[192:195], v[46:49]
	v_mfma_f32_16x16x32_bf16 v[42:45], v[138:141], v[192:195], v[42:45]
	v_mfma_f32_16x16x32_bf16 v[30:33], v[130:133], v[200:203], v[30:33]
	v_mfma_f32_16x16x32_bf16 v[26:29], v[138:141], v[200:203], v[26:29]
	v_mfma_f32_16x16x32_bf16 v[14:17], v[130:133], v[208:211], v[14:17]
	v_mfma_f32_16x16x32_bf16 v[10:13], v[138:141], v[208:211], v[10:13]
	v_mfma_f32_16x16x32_bf16 v[62:65], v[134:137], v[188:191], v[62:65]
	v_mfma_f32_16x16x32_bf16 v[58:61], v[142:145], v[188:191], v[58:61]
	v_mfma_f32_16x16x32_bf16 v[46:49], v[134:137], v[196:199], v[46:49]
	v_mfma_f32_16x16x32_bf16 v[42:45], v[142:145], v[196:199], v[42:45]
	v_mfma_f32_16x16x32_bf16 v[30:33], v[134:137], v[204:207], v[30:33]
	v_mfma_f32_16x16x32_bf16 v[26:29], v[142:145], v[204:207], v[26:29]
	v_mfma_f32_16x16x32_bf16 v[14:17], v[134:137], v[212:215], v[14:17]
	v_mfma_f32_16x16x32_bf16 v[10:13], v[142:145], v[212:215], v[10:13]
	v_mfma_f32_16x16x32_bf16 v[54:57], v[162:165], v[184:187], v[54:57]
	v_mfma_f32_16x16x32_bf16 v[50:53], v[176:179], v[184:187], v[50:53]
	v_mfma_f32_16x16x32_bf16 v[38:41], v[162:165], v[192:195], v[38:41]
	v_mfma_f32_16x16x32_bf16 v[34:37], v[176:179], v[192:195], v[34:37]
	v_mfma_f32_16x16x32_bf16 v[22:25], v[162:165], v[200:203], v[22:25]
	v_mfma_f32_16x16x32_bf16 v[18:21], v[176:179], v[200:203], v[18:21]
	v_mfma_f32_16x16x32_bf16 v[6:9], v[162:165], v[208:211], v[6:9]
	v_mfma_f32_16x16x32_bf16 v[2:5], v[176:179], v[208:211], v[2:5]
	v_mfma_f32_16x16x32_bf16 v[54:57], v[166:169], v[188:191], v[54:57]
	v_mfma_f32_16x16x32_bf16 v[50:53], v[180:183], v[188:191], v[50:53]
	v_mfma_f32_16x16x32_bf16 v[38:41], v[166:169], v[196:199], v[38:41]
	v_mfma_f32_16x16x32_bf16 v[34:37], v[180:183], v[196:199], v[34:37]
	v_mfma_f32_16x16x32_bf16 v[22:25], v[166:169], v[204:207], v[22:25]
	v_mfma_f32_16x16x32_bf16 v[18:21], v[180:183], v[204:207], v[18:21]
	v_mfma_f32_16x16x32_bf16 v[6:9], v[166:169], v[212:215], v[6:9]
	v_mfma_f32_16x16x32_bf16 v[2:5], v[180:183], v[212:215], v[2:5]
	s_barrier
; #define PG8_STAGE(bufoff, gbase, voff) do { _Pragma("unroll") for (int _i = 0; _i < 2; ++_i) \
;         __builtin_amdgcn_global_load_lds((const unsigned*)((const char*)(gbase) + (voff)[_i]), (PG8_LAS unsigned*)(lds + (bufoff) + ldsw + _i * 8192), 16, 0, 0); } while (0)
; #define PG8_LDA(dst, b, h) do { _Pragma("unroll") for (int m = 0; m < 4; ++m) _Pragma("unroll") for (int k = 0; k < 2; ++k) dst[m][k] = *(const PG8_LAS bf16x8*)(lds + PG8_SA(b, h) + aoff + m * 2048 + k * 1024); } while (0)
; #define PG8_LDB(dst, b, h) do { _Pragma("unroll") for (int n = 0; n < 2; ++n) _Pragma("unroll") for (int k = 0; k < 2; ++k) dst[n][k] = *(const PG8_LAS bf16x8*)(lds + PG8_SB(b, h) + boff + n * 2048 + k * 1024); } while (0)
; #define PG8_MMA(ai, bj, At, Bt) do { __builtin_amdgcn_s_setprio(1); _Pragma("unroll") for (int m = 0; m < 4; ++m) _Pragma("unroll") for (int n = 0; n < 2; ++n) _Pragma("unroll") for (int k = 0; k < 2; ++k) \
;         acc[ai][bj][m][n] = __builtin_amdgcn_mfma_f32_16x16x32_bf16(Bt[n][k], At[m][k], acc[ai][bj][m][n], 0, 0, 0); __builtin_amdgcn_s_setprio(0); } while (0)
; #define PG8_WAIT_V(n) asm volatile("s_waitcnt vmcnt(" #n ")" ::: "memory")
; #define PG8_WAIT_L(n) asm volatile("s_waitcnt lgkmcnt(" #n ")" ::: "memory")
; #define PG8_BAR __builtin_amdgcn_s_barrier()
; #define PG8_SCHED __builtin_amdgcn_sched_barrier(0)
; template <class Epi, class Sched, bool ALIGN_EPI = false, bool SP2 = false>
; __device__ __forceinline__ void gemm_phase(PG8_LAS unsigned char* lds, const Gemm g, const Sched& S, const Epi& E) {
;     ...
;             PG8_LDB(B0, 1, 0); PG8_LDB(B1, 1, 1); PG8_SCHED; PG8_LDA(At, 1, 0); PG8_STAGE(PG8_SA(0, 1), a2 + hA, voffA);
;             PG8_WAIT_V(8); PG8_WAIT_L(0); PG8_BAR; PG8_MMA(0, 0, At, B0); PG8_MMA(0, 1, At, B1); PG8_BAR; PG8_SCHED;
;             PG8_LDA(At, 1, 1); PG8_STAGE(PG8_SB(1, 0), b3, voffB); PG8_STAGE(PG8_SB(1, 1), b3 + hB, voffB); PG8_STAGE(PG8_SA(1, 0), a3, voffA);
;             PG8_WAIT_V(8); PG8_WAIT_L(0); PG8_BAR; PG8_MMA(1, 0, At, B0); PG8_MMA(1, 1, At, B1); PG8_BAR; PG8_SCHED;
	s_add_i32 s18, 0, 0x18000
	s_add_i32 s19, 0, 0x1c000
	v_add_u32_e32 v142, s18, v170
	v_add_u32_e32 v175, s19, v170
	ds_read_b128 v[130:133], v142
	ds_read_b128 v[134:137], v142 offset:1024
	ds_read_b128 v[138:141], v142 offset:2048
	ds_read_b128 v[142:145], v142 offset:3072
	ds_read_b128 v[162:165], v175
	ds_read_b128 v[166:169], v175 offset:1024
	ds_read_b128 v[176:179], v175 offset:2048
	ds_read_b128 v[180:183], v175 offset:3072
	s_add_u32 s48, s48, 0x80000
	s_addc_u32 s49, s49, 0
	s_mov_b32 m0, s60
	ds_read_b128 v[184:187], v174 offset:32768
	ds_read_b128 v[188:191], v174 offset:33792
	ds_read_b128 v[192:195], v174 offset:34816
	ds_read_b128 v[196:199], v174 offset:35840
	ds_read_b128 v[200:203], v174 offset:36864
	ds_read_b128 v[204:207], v174 offset:37888
	ds_read_b128 v[208:211], v174 offset:38912
	ds_read_b128 v[212:215], v174 offset:39936
	global_load_lds_dwordx4 v152, s[48:49]
	s_mov_b32 m0, s61
	s_nop 0
	global_load_lds_dwordx4 v148, s[48:49]
	s_waitcnt vmcnt(8)
	s_waitcnt lgkmcnt(0)
	s_barrier
	s_waitcnt lgkmcnt(0)
	v_mfma_f32_16x16x32_bf16 v[126:129], v[130:133], v[184:187], v[126:129]
	v_mfma_f32_16x16x32_bf16 v[122:125], v[138:141], v[184:187], v[122:125]
	v_mfma_f32_16x16x32_bf16 v[110:113], v[130:133], v[192:195], v[110:113]
	v_mfma_f32_16x16x32_bf16 v[106:109], v[138:141], v[192:195], v[106:109]
	v_mfma_f32_16x16x32_bf16 v[94:97], v[130:133], v[200:203], v[94:97]
	v_mfma_f32_16x16x32_bf16 v[90:93], v[138:141], v[200:203], v[90:93]
	v_mfma_f32_16x16x32_bf16 v[78:81], v[130:133], v[208:211], v[78:81]
	v_mfma_f32_16x16x32_bf16 v[74:77], v[138:141], v[208:211], v[74:77]
	v_mfma_f32_16x16x32_bf16 v[126:129], v[134:137], v[188:191], v[126:129]
	v_mfma_f32_16x16x32_bf16 v[122:125], v[142:145], v[188:191], v[122:125]
	v_mfma_f32_16x16x32_bf16 v[110:113], v[134:137], v[196:199], v[110:113]
	v_mfma_f32_16x16x32_bf16 v[106:109], v[142:145], v[196:199], v[106:109]
	v_mfma_f32_16x16x32_bf16 v[94:97], v[134:137], v[204:207], v[94:97]
	v_mfma_f32_16x16x32_bf16 v[90:93], v[142:145], v[204:207], v[90:93]
	v_mfma_f32_16x16x32_bf16 v[78:81], v[134:137], v[212:215], v[78:81]
	v_mfma_f32_16x16x32_bf16 v[74:77], v[142:145], v[212:215], v[74:77]
	v_mfma_f32_16x16x32_bf16 v[118:121], v[162:165], v[184:187], v[118:121]
	v_mfma_f32_16x16x32_bf16 v[114:117], v[176:179], v[184:187], v[114:117]
	v_mfma_f32_16x16x32_bf16 v[102:105], v[162:165], v[192:195], v[102:105]
	v_mfma_f32_16x16x32_bf16 v[98:101], v[176:179], v[192:195], v[98:101]
	v_mfma_f32_16x16x32_bf16 v[86:89], v[162:165], v[200:203], v[86:89]
	v_mfma_f32_16x16x32_bf16 v[82:85], v[176:179], v[200:203], v[82:85]
	v_mfma_f32_16x16x32_bf16 v[70:73], v[162:165], v[208:211], v[70:73]
	v_mfma_f32_16x16x32_bf16 v[66:69], v[176:179], v[208:211], v[66:69]
	v_mfma_f32_16x16x32_bf16 v[118:121], v[166:169], v[188:191], v[118:121]
	v_mfma_f32_16x16x32_bf16 v[114:117], v[180:183], v[188:191], v[114:117]
	v_mfma_f32_16x16x32_bf16 v[102:105], v[166:169], v[196:199], v[102:105]
	v_mfma_f32_16x16x32_bf16 v[98:101], v[180:183], v[196:199], v[98:101]
	v_mfma_f32_16x16x32_bf16 v[86:89], v[166:169], v[204:207], v[86:89]
	v_mfma_f32_16x16x32_bf16 v[82:85], v[180:183], v[204:207], v[82:85]
	v_mfma_f32_16x16x32_bf16 v[70:73], v[166:169], v[212:215], v[70:73]
	v_mfma_f32_16x16x32_bf16 v[66:69], v[180:183], v[212:215], v[66:69]
	s_barrier
	s_add_i32 s18, s18, s58
	s_mov_b32 m0, s18
	ds_read_b128 v[184:187], v174 offset:49152
	ds_read_b128 v[188:191], v174 offset:50176
	ds_read_b128 v[192:195], v174 offset:51200
	ds_read_b128 v[196:199], v174 offset:52224
	ds_read_b128 v[200:203], v174 offset:53248
	ds_read_b128 v[204:207], v174 offset:54272
	ds_read_b128 v[208:211], v174 offset:55296
	ds_read_b128 v[212:215], v174 offset:56320
	global_load_lds_dwordx4 v150, s[78:79]
	s_add_i32 m0, s18, 0x2000
	s_add_u32 s46, s46, 0x80080
	s_addc_u32 s47, s47, 0
	s_add_i32 s18, s19, s58
	global_load_lds_dwordx4 v146, s[78:79]
	s_mov_b32 m0, s18
	s_nop 0
	global_load_lds_dwordx4 v150, s[46:47]
	s_add_i32 m0, s18, 0x2000
	s_nop 0
	global_load_lds_dwordx4 v146, s[46:47]
	s_mov_b32 m0, s63
	s_nop 0
	global_load_lds_dwordx4 v152, s[80:81]
	s_mov_b32 m0, s64
	s_nop 0
	global_load_lds_dwordx4 v148, s[80:81]
	s_waitcnt vmcnt(8)
	s_waitcnt lgkmcnt(0)
	s_barrier
	s_waitcnt lgkmcnt(0)
	v_mfma_f32_16x16x32_bf16 v[62:65], v[130:133], v[184:187], v[62:65]
	v_mfma_f32_16x16x32_bf16 v[58:61], v[138:141], v[184:187], v[58:61]
	v_mfma_f32_16x16x32_bf16 v[46:49], v[130:133], v[192:195], v[46:49]
	v_mfma_f32_16x16x32_bf16 v[42:45], v[138:141], v[192:195], v[42:45]
	v_mfma_f32_16x16x32_bf16 v[30:33], v[130:133], v[200:203], v[30:33]
	v_mfma_f32_16x16x32_bf16 v[26:29], v[138:141], v[200:203], v[26:29]
	v_mfma_f32_16x16x32_bf16 v[14:17], v[130:133], v[208:211], v[14:17]
	v_mfma_f32_16x16x32_bf16 v[10:13], v[138:141], v[208:211], v[10:13]
	v_mfma_f32_16x16x32_bf16 v[62:65], v[134:137], v[188:191], v[62:65]
	v_mfma_f32_16x16x32_bf16 v[58:61], v[142:145], v[188:191], v[58:61]
	v_mfma_f32_16x16x32_bf16 v[46:49], v[134:137], v[196:199], v[46:49]
	v_mfma_f32_16x16x32_bf16 v[42:45], v[142:145], v[196:199], v[42:45]
	v_mfma_f32_16x16x32_bf16 v[30:33], v[134:137], v[204:207], v[30:33]
	v_mfma_f32_16x16x32_bf16 v[26:29], v[142:145], v[204:207], v[26:29]
	v_mfma_f32_16x16x32_bf16 v[14:17], v[134:137], v[212:215], v[14:17]
	v_mfma_f32_16x16x32_bf16 v[10:13], v[142:145], v[212:215], v[10:13]
	v_mfma_f32_16x16x32_bf16 v[54:57], v[162:165], v[184:187], v[54:57]
	v_mfma_f32_16x16x32_bf16 v[50:53], v[176:179], v[184:187], v[50:53]
	v_mfma_f32_16x16x32_bf16 v[38:41], v[162:165], v[192:195], v[38:41]
	v_mfma_f32_16x16x32_bf16 v[34:37], v[176:179], v[192:195], v[34:37]
	v_mfma_f32_16x16x32_bf16 v[22:25], v[162:165], v[200:203], v[22:25]
	v_mfma_f32_16x16x32_bf16 v[18:21], v[176:179], v[200:203], v[18:21]
	v_mfma_f32_16x16x32_bf16 v[6:9], v[162:165], v[208:211], v[6:9]
	v_mfma_f32_16x16x32_bf16 v[2:5], v[176:179], v[208:211], v[2:5]
	v_mfma_f32_16x16x32_bf16 v[54:57], v[166:169], v[188:191], v[54:57]
	v_mfma_f32_16x16x32_bf16 v[50:53], v[180:183], v[188:191], v[50:53]
	v_mfma_f32_16x16x32_bf16 v[38:41], v[166:169], v[196:199], v[38:41]
	v_mfma_f32_16x16x32_bf16 v[34:37], v[180:183], v[196:199], v[34:37]
	v_mfma_f32_16x16x32_bf16 v[22:25], v[166:169], v[204:207], v[22:25]
	v_mfma_f32_16x16x32_bf16 v[18:21], v[180:183], v[204:207], v[18:21]
	v_mfma_f32_16x16x32_bf16 v[6:9], v[166:169], v[212:215], v[6:9]
	v_mfma_f32_16x16x32_bf16 v[2:5], v[180:183], v[212:215], v[2:5]
	s_barrier
	s_add_i32 s74, s74, 2
	s_add_u32 s44, s44, 0x100
	s_addc_u32 s45, s45, 0
	s_add_u32 s72, s72, 0x100
	s_addc_u32 s73, s73, 0
	s_cmp_gt_u32 s74, 29
	s_cbranch_scc0 .LBB0_888
	s_and_b64 vcc, exec, s[20:21]
	s_cbranch_vccz .LBB0_891
	s_barrier

; #define PG8_STAGE(bufoff, gbase, voff) do { _Pragma("unroll") for (int _i = 0; _i < 2; ++_i) \
;         __builtin_amdgcn_global_load_lds((const unsigned*)((const char*)(gbase) + (voff)[_i]), (PG8_LAS unsigned*)(lds + (bufoff) + ldsw + _i * 8192), 16, 0, 0); } while (0)
; #define PG8_LDA(dst, b, h) do { _Pragma("unroll") for (int m = 0; m < 4; ++m) _Pragma("unroll") for (int k = 0; k < 2; ++k) dst[m][k] = *(const PG8_LAS bf16x8*)(lds + PG8_SA(b, h) + aoff + m * 2048 + k * 1024); } while (0)
; #define PG8_LDB(dst, b, h) do { _Pragma("unroll") for (int n = 0; n < 2; ++n) _Pragma("unroll") for (int k = 0; k < 2; ++k) dst[n][k] = *(const PG8_LAS bf16x8*)(lds + PG8_SB(b, h) + boff + n * 2048 + k * 1024); } while (0)
; #define PG8_MMA(ai, bj, At, Bt) do { __builtin_amdgcn_s_setprio(1); _Pragma("unroll") for (int m = 0; m < 4; ++m) _Pragma("unroll") for (int n = 0; n < 2; ++n) _Pragma("unroll") for (int k = 0; k < 2; ++k) \
;         acc[ai][bj][m][n] = __builtin_amdgcn_mfma_f32_16x16x32_bf16(Bt[n][k], At[m][k], acc[ai][bj][m][n], 0, 0, 0); __builtin_amdgcn_s_setprio(0); } while (0)
; #define PG8_WAIT_V(n) asm volatile("s_waitcnt vmcnt(" #n ")" ::: "memory")
; #define PG8_WAIT_L(n) asm volatile("s_waitcnt lgkmcnt(" #n ")" ::: "memory")
; #define PG8_BAR __builtin_amdgcn_s_barrier()
; #define PG8_SCHED __builtin_amdgcn_sched_barrier(0)
; template <class Epi, class Sched, bool ALIGN_EPI = false, bool SP2 = false>
; __device__ __forceinline__ void gemm_phase(PG8_LAS unsigned char* lds, const Gemm g, const Sched& S, const Epi& E) {
;     ...
;             PG8_LDB(B0, 0, 0); PG8_LDB(B1, 0, 1); PG8_SCHED; PG8_LDA(At, 0, 0); PG8_STAGE(PG8_SA(1, 1), a1 + hA, voffA);
;             PG8_WAIT_V(8); PG8_WAIT_L(0); PG8_BAR; PG8_MMA(0, 0, At, B0); PG8_MMA(0, 1, At, B1); PG8_BAR; PG8_SCHED;
;             PG8_LDA(At, 0, 1); PG8_STAGE(PG8_SB(0, 0), b2, voffB); PG8_STAGE(PG8_SB(0, 1), b2 + hB, voffB); PG8_STAGE(PG8_SA(0, 0), a2, voffA);
;             PG8_WAIT_V(8); PG8_WAIT_L(0); PG8_BAR; PG8_MMA(1, 0, At, B0); PG8_MMA(1, 1, At, B1); PG8_BAR; PG8_SCHED;
.LBB0_963:
	ds_read_b128 v[130:133], v208
	ds_read_b128 v[134:137], v208 offset:1024
	ds_read_b128 v[138:141], v208 offset:2048
	ds_read_b128 v[142:145], v208 offset:3072
	ds_read_b128 v[146:149], v209
	ds_read_b128 v[150:153], v209 offset:1024
	ds_read_b128 v[154:157], v209 offset:2048
	ds_read_b128 v[158:161], v209 offset:3072
	s_add_u32 s18, s48, 0xfff80080
	s_addc_u32 s19, s49, -1
	s_cmp_eq_u32 s78, 28
	s_cselect_b32 s53, s41, s19
	s_cselect_b32 s52, s47, s18
	s_cselect_b32 s51, s39, s77
	s_cselect_b32 s50, s75, s76
	s_add_i32 m0, s62, 0xc000
	ds_read_b128 v[162:165], v210
	ds_read_b128 v[166:169], v210 offset:1024
	ds_read_b128 v[170:173], v210 offset:2048
	ds_read_b128 v[174:177], v210 offset:3072
	ds_read_b128 v[194:197], v210 offset:4096
	ds_read_b128 v[198:201], v210 offset:5120
	ds_read_b128 v[202:205], v210 offset:6144
	ds_read_b128 v[212:215], v210 offset:7168
	global_load_lds_dwordx4 v186, s[48:49]
	s_add_i32 m0, s62, 0xe000
	s_nop 0
	global_load_lds_dwordx4 v188, s[48:49]
	s_waitcnt vmcnt(8)
	s_waitcnt lgkmcnt(0)
	s_barrier
	s_waitcnt lgkmcnt(0)
	v_mfma_f32_16x16x32_bf16 v[126:129], v[130:133], v[162:165], v[126:129]
	v_mfma_f32_16x16x32_bf16 v[122:125], v[138:141], v[162:165], v[122:125]
	v_mfma_f32_16x16x32_bf16 v[110:113], v[130:133], v[170:173], v[110:113]
	v_mfma_f32_16x16x32_bf16 v[106:109], v[138:141], v[170:173], v[106:109]
	v_mfma_f32_16x16x32_bf16 v[94:97], v[130:133], v[194:197], v[94:97]
	v_mfma_f32_16x16x32_bf16 v[90:93], v[138:141], v[194:197], v[90:93]
	v_mfma_f32_16x16x32_bf16 v[78:81], v[130:133], v[202:205], v[78:81]
	v_mfma_f32_16x16x32_bf16 v[74:77], v[138:141], v[202:205], v[74:77]
	v_mfma_f32_16x16x32_bf16 v[126:129], v[134:137], v[166:169], v[126:129]
	v_mfma_f32_16x16x32_bf16 v[122:125], v[142:145], v[166:169], v[122:125]
	v_mfma_f32_16x16x32_bf16 v[110:113], v[134:137], v[174:177], v[110:113]
	v_mfma_f32_16x16x32_bf16 v[106:109], v[142:145], v[174:177], v[106:109]
	v_mfma_f32_16x16x32_bf16 v[94:97], v[134:137], v[198:201], v[94:97]
	v_mfma_f32_16x16x32_bf16 v[90:93], v[142:145], v[198:201], v[90:93]
	v_mfma_f32_16x16x32_bf16 v[78:81], v[134:137], v[212:215], v[78:81]
	v_mfma_f32_16x16x32_bf16 v[74:77], v[142:145], v[212:215], v[74:77]
	v_mfma_f32_16x16x32_bf16 v[118:121], v[146:149], v[162:165], v[118:121]
	v_mfma_f32_16x16x32_bf16 v[114:117], v[154:157], v[162:165], v[114:117]
	v_mfma_f32_16x16x32_bf16 v[102:105], v[146:149], v[170:173], v[102:105]
	v_mfma_f32_16x16x32_bf16 v[98:101], v[154:157], v[170:173], v[98:101]
	v_mfma_f32_16x16x32_bf16 v[86:89], v[146:149], v[194:197], v[86:89]
	v_mfma_f32_16x16x32_bf16 v[82:85], v[154:157], v[194:197], v[82:85]
	v_mfma_f32_16x16x32_bf16 v[70:73], v[146:149], v[202:205], v[70:73]
	v_mfma_f32_16x16x32_bf16 v[66:69], v[154:157], v[202:205], v[66:69]
	v_mfma_f32_16x16x32_bf16 v[118:121], v[150:153], v[166:169], v[118:121]
	v_mfma_f32_16x16x32_bf16 v[114:117], v[158:161], v[166:169], v[114:117]
	v_mfma_f32_16x16x32_bf16 v[102:105], v[150:153], v[174:177], v[102:105]
	v_mfma_f32_16x16x32_bf16 v[98:101], v[158:161], v[174:177], v[98:101]
	v_mfma_f32_16x16x32_bf16 v[86:89], v[150:153], v[198:201], v[86:89]
	v_mfma_f32_16x16x32_bf16 v[82:85], v[158:161], v[198:201], v[82:85]
	v_mfma_f32_16x16x32_bf16 v[70:73], v[150:153], v[212:215], v[70:73]
	v_mfma_f32_16x16x32_bf16 v[66:69], v[158:161], v[212:215], v[66:69]
	s_barrier
	s_add_i32 s18, s72, s61
	s_add_u32 s82, s50, s22
	s_addc_u32 s83, s51, s23
	s_mov_b32 m0, s18
	ds_read_b128 v[162:165], v210 offset:16384
	ds_read_b128 v[166:169], v210 offset:17408
	ds_read_b128 v[170:173], v210 offset:18432
	ds_read_b128 v[174:177], v210 offset:19456
	ds_read_b128 v[194:197], v210 offset:20480
	ds_read_b128 v[198:201], v210 offset:21504
	ds_read_b128 v[202:205], v210 offset:22528
	ds_read_b128 v[212:215], v210 offset:23552
	global_load_lds_dwordx4 v180, s[50:51]
	s_add_i32 m0, s18, 0x2000
	s_add_u32 s80, s50, 0x80000
	s_addc_u32 s81, s51, 0
	s_add_i32 s18, s73, s61
	global_load_lds_dwordx4 v184, s[50:51]
	s_mov_b32 m0, s18
	s_nop 0
	global_load_lds_dwordx4 v180, s[80:81]
	s_add_i32 m0, s18, 0x2000
	s_nop 0
	global_load_lds_dwordx4 v184, s[80:81]
	s_add_u32 s88, s52, s22
	s_addc_u32 s89, s53, s23
	s_mov_b32 m0, s62
	s_nop 0
	global_load_lds_dwordx4 v178, s[52:53]
	s_mov_b32 m0, s63
	s_nop 0
	global_load_lds_dwordx4 v182, s[52:53]
	s_waitcnt vmcnt(8)
	s_waitcnt lgkmcnt(0)
	s_barrier
	s_waitcnt lgkmcnt(0)
	v_mfma_f32_16x16x32_bf16 v[62:65], v[130:133], v[162:165], v[62:65]
	v_mfma_f32_16x16x32_bf16 v[58:61], v[138:141], v[162:165], v[58:61]
	v_mfma_f32_16x16x32_bf16 v[46:49], v[130:133], v[170:173], v[46:49]
	v_mfma_f32_16x16x32_bf16 v[42:45], v[138:141], v[170:173], v[42:45]
	v_mfma_f32_16x16x32_bf16 v[30:33], v[130:133], v[194:197], v[30:33]
	v_mfma_f32_16x16x32_bf16 v[26:29], v[138:141], v[194:197], v[26:29]
	v_mfma_f32_16x16x32_bf16 v[14:17], v[130:133], v[202:205], v[14:17]
	v_mfma_f32_16x16x32_bf16 v[10:13], v[138:141], v[202:205], v[10:13]
	v_mfma_f32_16x16x32_bf16 v[62:65], v[134:137], v[166:169], v[62:65]
	v_mfma_f32_16x16x32_bf16 v[58:61], v[142:145], v[166:169], v[58:61]
	v_mfma_f32_16x16x32_bf16 v[46:49], v[134:137], v[174:177], v[46:49]
	v_mfma_f32_16x16x32_bf16 v[42:45], v[142:145], v[174:177], v[42:45]
	v_mfma_f32_16x16x32_bf16 v[30:33], v[134:137], v[198:201], v[30:33]
	v_mfma_f32_16x16x32_bf16 v[26:29], v[142:145], v[198:201], v[26:29]
	v_mfma_f32_16x16x32_bf16 v[14:17], v[134:137], v[212:215], v[14:17]
	v_mfma_f32_16x16x32_bf16 v[10:13], v[142:145], v[212:215], v[10:13]
	v_mfma_f32_16x16x32_bf16 v[54:57], v[146:149], v[162:165], v[54:57]
	v_mfma_f32_16x16x32_bf16 v[50:53], v[154:157], v[162:165], v[50:53]
	v_mfma_f32_16x16x32_bf16 v[38:41], v[146:149], v[170:173], v[38:41]
	v_mfma_f32_16x16x32_bf16 v[34:37], v[154:157], v[170:173], v[34:37]
	v_mfma_f32_16x16x32_bf16 v[22:25], v[146:149], v[194:197], v[22:25]
	v_mfma_f32_16x16x32_bf16 v[18:21], v[154:157], v[194:197], v[18:21]
	v_mfma_f32_16x16x32_bf16 v[6:9], v[146:149], v[202:205], v[6:9]
	v_mfma_f32_16x16x32_bf16 v[2:5], v[154:157], v[202:205], v[2:5]
	v_mfma_f32_16x16x32_bf16 v[54:57], v[150:153], v[166:169], v[54:57]
	v_mfma_f32_16x16x32_bf16 v[50:53], v[158:161], v[166:169], v[50:53]
	v_mfma_f32_16x16x32_bf16 v[38:41], v[150:153], v[174:177], v[38:41]
	v_mfma_f32_16x16x32_bf16 v[34:37], v[158:161], v[174:177], v[34:37]
	v_mfma_f32_16x16x32_bf16 v[22:25], v[150:153], v[198:201], v[22:25]
	v_mfma_f32_16x16x32_bf16 v[18:21], v[158:161], v[198:201], v[18:21]
	v_mfma_f32_16x16x32_bf16 v[6:9], v[150:153], v[212:215], v[6:9]
	v_mfma_f32_16x16x32_bf16 v[2:5], v[158:161], v[212:215], v[2:5]
	s_barrier
; #define PG8_STAGE(bufoff, gbase, voff) do { _Pragma("unroll") for (int _i = 0; _i < 2; ++_i) \
;         __builtin_amdgcn_global_load_lds((const unsigned*)((const char*)(gbase) + (voff)[_i]), (PG8_LAS unsigned*)(lds + (bufoff) + ldsw + _i * 8192), 16, 0, 0); } while (0)
; #define PG8_LDA(dst, b, h) do { _Pragma("unroll") for (int m = 0; m < 4; ++m) _Pragma("unroll") for (int k = 0; k < 2; ++k) dst[m][k] = *(const PG8_LAS bf16x8*)(lds + PG8_SA(b, h) + aoff + m * 2048 + k * 1024); } while (0)
; #define PG8_LDB(dst, b, h) do { _Pragma("unroll") for (int n = 0; n < 2; ++n) _Pragma("unroll") for (int k = 0; k < 2; ++k) dst[n][k] = *(const PG8_LAS bf16x8*)(lds + PG8_SB(b, h) + boff + n * 2048 + k * 1024); } while (0)
; #define PG8_MMA(ai, bj, At, Bt) do { __builtin_amdgcn_s_setprio(1); _Pragma("unroll") for (int m = 0; m < 4; ++m) _Pragma("unroll") for (int n = 0; n < 2; ++n) _Pragma("unroll") for (int k = 0; k < 2; ++k) \
;         acc[ai][bj][m][n] = __builtin_amdgcn_mfma_f32_16x16x32_bf16(Bt[n][k], At[m][k], acc[ai][bj][m][n], 0, 0, 0); __builtin_amdgcn_s_setprio(0); } while (0)
; #define PG8_WAIT_V(n) asm volatile("s_waitcnt vmcnt(" #n ")" ::: "memory")
; #define PG8_WAIT_L(n) asm volatile("s_waitcnt lgkmcnt(" #n ")" ::: "memory")
; #define PG8_BAR __builtin_amdgcn_s_barrier()
; #define PG8_SCHED __builtin_amdgcn_sched_barrier(0)
; template <class Epi, class Sched, bool ALIGN_EPI = false, bool SP2 = false>
; __device__ __forceinline__ void gemm_phase(PG8_LAS unsigned char* lds, const Gemm g, const Sched& S, const Epi& E) {
;     ...
;             PG8_LDB(B0, 1, 0); PG8_LDB(B1, 1, 1); PG8_SCHED; PG8_LDA(At, 1, 0); PG8_STAGE(PG8_SA(0, 1), a2 + hA, voffA);
;             PG8_WAIT_V(8); PG8_WAIT_L(0); PG8_BAR; PG8_MMA(0, 0, At, B0); PG8_MMA(0, 1, At, B1); PG8_BAR; PG8_SCHED;
;             PG8_LDA(At, 1, 1); PG8_STAGE(PG8_SB(1, 0), b3, voffB); PG8_STAGE(PG8_SB(1, 1), b3 + hB, voffB); PG8_STAGE(PG8_SA(1, 0), a3, voffA);
;             PG8_WAIT_V(8); PG8_WAIT_L(0); PG8_BAR; PG8_MMA(1, 0, At, B0); PG8_MMA(1, 1, At, B1); PG8_BAR; PG8_SCHED;
	s_add_i32 s18, 0, 0x18000
	s_add_i32 s19, 0, 0x1c000
	v_add_u32_e32 v142, s18, v206
	v_add_u32_e32 v158, s19, v206
	ds_read_b128 v[130:133], v142
	ds_read_b128 v[134:137], v142 offset:1024
	ds_read_b128 v[138:141], v142 offset:2048
	ds_read_b128 v[142:145], v142 offset:3072
	ds_read_b128 v[146:149], v158
	ds_read_b128 v[150:153], v158 offset:1024
	ds_read_b128 v[154:157], v158 offset:2048
	ds_read_b128 v[158:161], v158 offset:3072
	s_add_u32 s52, s52, 0x80000
	s_addc_u32 s53, s53, 0
	s_mov_b32 m0, s64
	ds_read_b128 v[162:165], v210 offset:32768
	ds_read_b128 v[166:169], v210 offset:33792
	ds_read_b128 v[170:173], v210 offset:34816
	ds_read_b128 v[174:177], v210 offset:35840
	ds_read_b128 v[194:197], v210 offset:36864
	ds_read_b128 v[198:201], v210 offset:37888
	ds_read_b128 v[202:205], v210 offset:38912
	ds_read_b128 v[212:215], v210 offset:39936
	global_load_lds_dwordx4 v178, s[52:53]
	s_mov_b32 m0, s65
	s_nop 0
	global_load_lds_dwordx4 v182, s[52:53]
	s_waitcnt vmcnt(8)
	s_waitcnt lgkmcnt(0)
	s_barrier
	s_waitcnt lgkmcnt(0)
	v_mfma_f32_16x16x32_bf16 v[126:129], v[130:133], v[162:165], v[126:129]
	v_mfma_f32_16x16x32_bf16 v[122:125], v[138:141], v[162:165], v[122:125]
	v_mfma_f32_16x16x32_bf16 v[110:113], v[130:133], v[170:173], v[110:113]
	v_mfma_f32_16x16x32_bf16 v[106:109], v[138:141], v[170:173], v[106:109]
	v_mfma_f32_16x16x32_bf16 v[94:97], v[130:133], v[194:197], v[94:97]
	v_mfma_f32_16x16x32_bf16 v[90:93], v[138:141], v[194:197], v[90:93]
	v_mfma_f32_16x16x32_bf16 v[78:81], v[130:133], v[202:205], v[78:81]
	v_mfma_f32_16x16x32_bf16 v[74:77], v[138:141], v[202:205], v[74:77]
	v_mfma_f32_16x16x32_bf16 v[126:129], v[134:137], v[166:169], v[126:129]
	v_mfma_f32_16x16x32_bf16 v[122:125], v[142:145], v[166:169], v[122:125]
	v_mfma_f32_16x16x32_bf16 v[110:113], v[134:137], v[174:177], v[110:113]
	v_mfma_f32_16x16x32_bf16 v[106:109], v[142:145], v[174:177], v[106:109]
	v_mfma_f32_16x16x32_bf16 v[94:97], v[134:137], v[198:201], v[94:97]
	v_mfma_f32_16x16x32_bf16 v[90:93], v[142:145], v[198:201], v[90:93]
	v_mfma_f32_16x16x32_bf16 v[78:81], v[134:137], v[212:215], v[78:81]
	v_mfma_f32_16x16x32_bf16 v[74:77], v[142:145], v[212:215], v[74:77]
	v_mfma_f32_16x16x32_bf16 v[118:121], v[146:149], v[162:165], v[118:121]
	v_mfma_f32_16x16x32_bf16 v[114:117], v[154:157], v[162:165], v[114:117]
	v_mfma_f32_16x16x32_bf16 v[102:105], v[146:149], v[170:173], v[102:105]
	v_mfma_f32_16x16x32_bf16 v[98:101], v[154:157], v[170:173], v[98:101]
	v_mfma_f32_16x16x32_bf16 v[86:89], v[146:149], v[194:197], v[86:89]
	v_mfma_f32_16x16x32_bf16 v[82:85], v[154:157], v[194:197], v[82:85]
	v_mfma_f32_16x16x32_bf16 v[70:73], v[146:149], v[202:205], v[70:73]
	v_mfma_f32_16x16x32_bf16 v[66:69], v[154:157], v[202:205], v[66:69]
	v_mfma_f32_16x16x32_bf16 v[118:121], v[150:153], v[166:169], v[118:121]
	v_mfma_f32_16x16x32_bf16 v[114:117], v[158:161], v[166:169], v[114:117]
	v_mfma_f32_16x16x32_bf16 v[102:105], v[150:153], v[174:177], v[102:105]
	v_mfma_f32_16x16x32_bf16 v[98:101], v[158:161], v[174:177], v[98:101]
	v_mfma_f32_16x16x32_bf16 v[86:89], v[150:153], v[198:201], v[86:89]
	v_mfma_f32_16x16x32_bf16 v[82:85], v[158:161], v[198:201], v[82:85]
	v_mfma_f32_16x16x32_bf16 v[70:73], v[150:153], v[212:215], v[70:73]
	v_mfma_f32_16x16x32_bf16 v[66:69], v[158:161], v[212:215], v[66:69]
	s_barrier
	s_add_i32 s18, s18, s61
	s_mov_b32 m0, s18
	ds_read_b128 v[162:165], v210 offset:49152
	ds_read_b128 v[166:169], v210 offset:50176
	ds_read_b128 v[170:173], v210 offset:51200
	ds_read_b128 v[174:177], v210 offset:52224
	ds_read_b128 v[194:197], v210 offset:53248
	ds_read_b128 v[198:201], v210 offset:54272
	ds_read_b128 v[202:205], v210 offset:55296
	ds_read_b128 v[212:215], v210 offset:56320
	global_load_lds_dwordx4 v180, s[82:83]
	s_add_i32 m0, s18, 0x2000
	s_add_u32 s50, s50, 0x80080
	s_addc_u32 s51, s51, 0
	s_add_i32 s18, s19, s61
	global_load_lds_dwordx4 v184, s[82:83]
	s_mov_b32 m0, s18
	s_nop 0
	global_load_lds_dwordx4 v180, s[50:51]
	s_add_i32 m0, s18, 0x2000
	s_nop 0
	global_load_lds_dwordx4 v184, s[50:51]
	s_mov_b32 m0, s69
	s_nop 0
	global_load_lds_dwordx4 v178, s[88:89]
	s_mov_b32 m0, s70
	s_nop 0
	global_load_lds_dwordx4 v182, s[88:89]
	s_waitcnt vmcnt(8)
	s_waitcnt lgkmcnt(0)
	s_barrier
	s_waitcnt lgkmcnt(0)
	v_mfma_f32_16x16x32_bf16 v[62:65], v[130:133], v[162:165], v[62:65]
	v_mfma_f32_16x16x32_bf16 v[58:61], v[138:141], v[162:165], v[58:61]
	v_mfma_f32_16x16x32_bf16 v[46:49], v[130:133], v[170:173], v[46:49]
	v_mfma_f32_16x16x32_bf16 v[42:45], v[138:141], v[170:173], v[42:45]
	v_mfma_f32_16x16x32_bf16 v[30:33], v[130:133], v[194:197], v[30:33]
	v_mfma_f32_16x16x32_bf16 v[26:29], v[138:141], v[194:197], v[26:29]
	v_mfma_f32_16x16x32_bf16 v[14:17], v[130:133], v[202:205], v[14:17]
	v_mfma_f32_16x16x32_bf16 v[10:13], v[138:141], v[202:205], v[10:13]
	v_mfma_f32_16x16x32_bf16 v[62:65], v[134:137], v[166:169], v[62:65]
	v_mfma_f32_16x16x32_bf16 v[58:61], v[142:145], v[166:169], v[58:61]
	v_mfma_f32_16x16x32_bf16 v[46:49], v[134:137], v[174:177], v[46:49]
	v_mfma_f32_16x16x32_bf16 v[42:45], v[142:145], v[174:177], v[42:45]
	v_mfma_f32_16x16x32_bf16 v[30:33], v[134:137], v[198:201], v[30:33]
	v_mfma_f32_16x16x32_bf16 v[26:29], v[142:145], v[198:201], v[26:29]
	v_mfma_f32_16x16x32_bf16 v[14:17], v[134:137], v[212:215], v[14:17]
	v_mfma_f32_16x16x32_bf16 v[10:13], v[142:145], v[212:215], v[10:13]
	v_mfma_f32_16x16x32_bf16 v[54:57], v[146:149], v[162:165], v[54:57]
	v_mfma_f32_16x16x32_bf16 v[50:53], v[154:157], v[162:165], v[50:53]
	v_mfma_f32_16x16x32_bf16 v[38:41], v[146:149], v[170:173], v[38:41]
	v_mfma_f32_16x16x32_bf16 v[34:37], v[154:157], v[170:173], v[34:37]
	v_mfma_f32_16x16x32_bf16 v[22:25], v[146:149], v[194:197], v[22:25]
	v_mfma_f32_16x16x32_bf16 v[18:21], v[154:157], v[194:197], v[18:21]
	v_mfma_f32_16x16x32_bf16 v[6:9], v[146:149], v[202:205], v[6:9]
	v_mfma_f32_16x16x32_bf16 v[2:5], v[154:157], v[202:205], v[2:5]
	v_mfma_f32_16x16x32_bf16 v[54:57], v[150:153], v[166:169], v[54:57]
	v_mfma_f32_16x16x32_bf16 v[50:53], v[158:161], v[166:169], v[50:53]
	v_mfma_f32_16x16x32_bf16 v[38:41], v[150:153], v[174:177], v[38:41]
	v_mfma_f32_16x16x32_bf16 v[34:37], v[158:161], v[174:177], v[34:37]
	v_mfma_f32_16x16x32_bf16 v[22:25], v[150:153], v[198:201], v[22:25]
	v_mfma_f32_16x16x32_bf16 v[18:21], v[158:161], v[198:201], v[18:21]
	v_mfma_f32_16x16x32_bf16 v[6:9], v[150:153], v[212:215], v[6:9]
	v_mfma_f32_16x16x32_bf16 v[2:5], v[158:161], v[212:215], v[2:5]
	s_barrier
	s_add_i32 s78, s78, 2
	s_add_u32 s48, s48, 0x100
	s_addc_u32 s49, s49, 0
	s_add_u32 s76, s76, 0x100
	s_addc_u32 s77, s77, 0
	s_cmp_gt_u32 s78, 29
	s_cbranch_scc0 .LBB0_963
	s_and_b64 vcc, exec, s[24:25]
	s_cbranch_vccz .LBB0_966
	s_barrier

; #define PG8_STAGE(bufoff, gbase, voff) do { _Pragma("unroll") for (int _i = 0; _i < 2; ++_i) \
;         __builtin_amdgcn_global_load_lds((const unsigned*)((const char*)(gbase) + (voff)[_i]), (PG8_LAS unsigned*)(lds + (bufoff) + ldsw + _i * 8192), 16, 0, 0); } while (0)
; #define PG8_LDA(dst, b, h) do { _Pragma("unroll") for (int m = 0; m < 4; ++m) _Pragma("unroll") for (int k = 0; k < 2; ++k) dst[m][k] = *(const PG8_LAS bf16x8*)(lds + PG8_SA(b, h) + aoff + m * 2048 + k * 1024); } while (0)
; #define PG8_LDB(dst, b, h) do { _Pragma("unroll") for (int n = 0; n < 2; ++n) _Pragma("unroll") for (int k = 0; k < 2; ++k) dst[n][k] = *(const PG8_LAS bf16x8*)(lds + PG8_SB(b, h) + boff + n * 2048 + k * 1024); } while (0)
; #define PG8_MMA(ai, bj, At, Bt) do { __builtin_amdgcn_s_setprio(1); _Pragma("unroll") for (int m = 0; m < 4; ++m) _Pragma("unroll") for (int n = 0; n < 2; ++n) _Pragma("unroll") for (int k = 0; k < 2; ++k) \
;         acc[ai][bj][m][n] = __builtin_amdgcn_mfma_f32_16x16x32_bf16(Bt[n][k], At[m][k], acc[ai][bj][m][n], 0, 0, 0); __builtin_amdgcn_s_setprio(0); } while (0)
; #define PG8_WAIT_V(n) asm volatile("s_waitcnt vmcnt(" #n ")" ::: "memory")
; #define PG8_WAIT_L(n) asm volatile("s_waitcnt lgkmcnt(" #n ")" ::: "memory")
; #define PG8_BAR __builtin_amdgcn_s_barrier()
; #define PG8_SCHED __builtin_amdgcn_sched_barrier(0)
; template <class Epi, class Sched, bool ALIGN_EPI = false, bool SP2 = false>
; __device__ __forceinline__ void gemm_phase(PG8_LAS unsigned char* lds, const Gemm g, const Sched& S, const Epi& E) {
;     ...
;             PG8_LDB(B0, 0, 0); PG8_LDB(B1, 0, 1); PG8_SCHED; PG8_LDA(At, 0, 0); PG8_STAGE(PG8_SA(1, 1), a1 + hA, voffA);
;             PG8_WAIT_V(8); PG8_WAIT_L(0); PG8_BAR; PG8_MMA(0, 0, At, B0); PG8_MMA(0, 1, At, B1); PG8_BAR; PG8_SCHED;
;             PG8_LDA(At, 0, 1); PG8_STAGE(PG8_SB(0, 0), b2, voffB); PG8_STAGE(PG8_SB(0, 1), b2 + hB, voffB); PG8_STAGE(PG8_SA(0, 0), a2, voffA);
;             PG8_WAIT_V(8); PG8_WAIT_L(0); PG8_BAR; PG8_MMA(1, 0, At, B0); PG8_MMA(1, 1, At, B1); PG8_BAR; PG8_SCHED;
.LBB0_1048:
	ds_read_b128 v[148:151], v169
	ds_read_b128 v[152:155], v169 offset:1024
	ds_read_b128 v[156:159], v169 offset:2048
	ds_read_b128 v[160:163], v169 offset:3072
	ds_read_b128 v[180:183], v171
	ds_read_b128 v[184:187], v171 offset:1024
	ds_read_b128 v[188:191], v171 offset:2048
	ds_read_b128 v[192:195], v171 offset:3072
	s_add_u32 s18, s8, 0xfff80080
	s_addc_u32 s19, s9, -1
	s_cmp_eq_u32 s72, 28
	s_cselect_b32 s45, s1, s19
	s_cselect_b32 s44, s37, s18
	s_cselect_b32 s43, s25, s71
	s_cselect_b32 s42, s69, s70
	s_add_i32 m0, s51, 0xc000
	ds_read_b128 v[196:199], v173
	ds_read_b128 v[200:203], v173 offset:1024
	ds_read_b128 v[204:207], v173 offset:2048
	ds_read_b128 v[208:211], v173 offset:3072
	ds_read_b128 v[212:215], v173 offset:4096
	ds_read_b128 v[216:219], v173 offset:5120
	ds_read_b128 v[224:227], v173 offset:6144
	ds_read_b128 v[228:231], v173 offset:7168
	global_load_lds_dwordx4 v140, s[8:9]
	s_add_i32 m0, s51, 0xe000
	s_nop 0
	global_load_lds_dwordx4 v142, s[8:9]
	s_waitcnt vmcnt(8)
	s_waitcnt lgkmcnt(0)
	s_barrier
	s_waitcnt lgkmcnt(0)
	v_mfma_f32_16x16x32_bf16 v[126:129], v[148:151], v[196:199], v[126:129]
	v_mfma_f32_16x16x32_bf16 v[122:125], v[156:159], v[196:199], v[122:125]
	v_mfma_f32_16x16x32_bf16 v[110:113], v[148:151], v[204:207], v[110:113]
	v_mfma_f32_16x16x32_bf16 v[106:109], v[156:159], v[204:207], v[106:109]
	v_mfma_f32_16x16x32_bf16 v[94:97], v[148:151], v[212:215], v[94:97]
	v_mfma_f32_16x16x32_bf16 v[90:93], v[156:159], v[212:215], v[90:93]
	v_mfma_f32_16x16x32_bf16 v[78:81], v[148:151], v[224:227], v[78:81]
	v_mfma_f32_16x16x32_bf16 v[74:77], v[156:159], v[224:227], v[74:77]
	v_mfma_f32_16x16x32_bf16 v[126:129], v[152:155], v[200:203], v[126:129]
	v_mfma_f32_16x16x32_bf16 v[122:125], v[160:163], v[200:203], v[122:125]
	v_mfma_f32_16x16x32_bf16 v[110:113], v[152:155], v[208:211], v[110:113]
	v_mfma_f32_16x16x32_bf16 v[106:109], v[160:163], v[208:211], v[106:109]
	v_mfma_f32_16x16x32_bf16 v[94:97], v[152:155], v[216:219], v[94:97]
	v_mfma_f32_16x16x32_bf16 v[90:93], v[160:163], v[216:219], v[90:93]
	v_mfma_f32_16x16x32_bf16 v[78:81], v[152:155], v[228:231], v[78:81]
	v_mfma_f32_16x16x32_bf16 v[74:77], v[160:163], v[228:231], v[74:77]
	v_mfma_f32_16x16x32_bf16 v[118:121], v[180:183], v[196:199], v[118:121]
	v_mfma_f32_16x16x32_bf16 v[114:117], v[188:191], v[196:199], v[114:117]
	v_mfma_f32_16x16x32_bf16 v[102:105], v[180:183], v[204:207], v[102:105]
	v_mfma_f32_16x16x32_bf16 v[98:101], v[188:191], v[204:207], v[98:101]
	v_mfma_f32_16x16x32_bf16 v[86:89], v[180:183], v[212:215], v[86:89]
	v_mfma_f32_16x16x32_bf16 v[82:85], v[188:191], v[212:215], v[82:85]
	v_mfma_f32_16x16x32_bf16 v[70:73], v[180:183], v[224:227], v[70:73]
	v_mfma_f32_16x16x32_bf16 v[66:69], v[188:191], v[224:227], v[66:69]
	v_mfma_f32_16x16x32_bf16 v[118:121], v[184:187], v[200:203], v[118:121]
	v_mfma_f32_16x16x32_bf16 v[114:117], v[192:195], v[200:203], v[114:117]
	v_mfma_f32_16x16x32_bf16 v[102:105], v[184:187], v[208:211], v[102:105]
	v_mfma_f32_16x16x32_bf16 v[98:101], v[192:195], v[208:211], v[98:101]
	v_mfma_f32_16x16x32_bf16 v[86:89], v[184:187], v[216:219], v[86:89]
	v_mfma_f32_16x16x32_bf16 v[82:85], v[192:195], v[216:219], v[82:85]
	v_mfma_f32_16x16x32_bf16 v[70:73], v[184:187], v[228:231], v[70:73]
	v_mfma_f32_16x16x32_bf16 v[66:69], v[192:195], v[228:231], v[66:69]
	s_barrier
	s_add_i32 s18, s63, s49
	s_add_u32 s76, s42, s20
	s_addc_u32 s77, s43, s21
	s_mov_b32 m0, s18
	ds_read_b128 v[196:199], v173 offset:16384
	ds_read_b128 v[200:203], v173 offset:17408
	ds_read_b128 v[204:207], v173 offset:18432
	ds_read_b128 v[208:211], v173 offset:19456
	ds_read_b128 v[212:215], v173 offset:20480
	ds_read_b128 v[216:219], v173 offset:21504
	ds_read_b128 v[224:227], v173 offset:22528
	ds_read_b128 v[228:231], v173 offset:23552
	global_load_lds_dwordx4 v134, s[42:43]
	s_add_i32 m0, s18, 0x2000
	s_add_u32 s74, s42, 0x80000
	s_addc_u32 s75, s43, 0
	s_add_i32 s18, s64, s49
	global_load_lds_dwordx4 v130, s[42:43]
	s_mov_b32 m0, s18
	s_nop 0
	global_load_lds_dwordx4 v134, s[74:75]
	s_add_i32 m0, s18, 0x2000
	s_nop 0
	global_load_lds_dwordx4 v130, s[74:75]
	s_add_u32 s78, s44, s20
	s_addc_u32 s79, s45, s21
	s_mov_b32 m0, s51
	s_nop 0
	global_load_lds_dwordx4 v136, s[44:45]
	s_mov_b32 m0, s52
	s_nop 0
	global_load_lds_dwordx4 v132, s[44:45]
	s_waitcnt vmcnt(8)
	s_waitcnt lgkmcnt(0)
	s_barrier
	s_waitcnt lgkmcnt(0)
	v_mfma_f32_16x16x32_bf16 v[62:65], v[148:151], v[196:199], v[62:65]
	v_mfma_f32_16x16x32_bf16 v[58:61], v[156:159], v[196:199], v[58:61]
	v_mfma_f32_16x16x32_bf16 v[46:49], v[148:151], v[204:207], v[46:49]
	v_mfma_f32_16x16x32_bf16 v[42:45], v[156:159], v[204:207], v[42:45]
	v_mfma_f32_16x16x32_bf16 v[30:33], v[148:151], v[212:215], v[30:33]
	v_mfma_f32_16x16x32_bf16 v[26:29], v[156:159], v[212:215], v[26:29]
	v_mfma_f32_16x16x32_bf16 v[14:17], v[148:151], v[224:227], v[14:17]
	v_mfma_f32_16x16x32_bf16 v[10:13], v[156:159], v[224:227], v[10:13]
	v_mfma_f32_16x16x32_bf16 v[62:65], v[152:155], v[200:203], v[62:65]
	v_mfma_f32_16x16x32_bf16 v[58:61], v[160:163], v[200:203], v[58:61]
	v_mfma_f32_16x16x32_bf16 v[46:49], v[152:155], v[208:211], v[46:49]
	v_mfma_f32_16x16x32_bf16 v[42:45], v[160:163], v[208:211], v[42:45]
	v_mfma_f32_16x16x32_bf16 v[30:33], v[152:155], v[216:219], v[30:33]
	v_mfma_f32_16x16x32_bf16 v[26:29], v[160:163], v[216:219], v[26:29]
	v_mfma_f32_16x16x32_bf16 v[14:17], v[152:155], v[228:231], v[14:17]
	v_mfma_f32_16x16x32_bf16 v[10:13], v[160:163], v[228:231], v[10:13]
	v_mfma_f32_16x16x32_bf16 v[54:57], v[180:183], v[196:199], v[54:57]
	v_mfma_f32_16x16x32_bf16 v[50:53], v[188:191], v[196:199], v[50:53]
	v_mfma_f32_16x16x32_bf16 v[38:41], v[180:183], v[204:207], v[38:41]
	v_mfma_f32_16x16x32_bf16 v[34:37], v[188:191], v[204:207], v[34:37]
	v_mfma_f32_16x16x32_bf16 v[22:25], v[180:183], v[212:215], v[22:25]
	v_mfma_f32_16x16x32_bf16 v[18:21], v[188:191], v[212:215], v[18:21]
	v_mfma_f32_16x16x32_bf16 v[6:9], v[180:183], v[224:227], v[6:9]
	v_mfma_f32_16x16x32_bf16 v[2:5], v[188:191], v[224:227], v[2:5]
	v_mfma_f32_16x16x32_bf16 v[54:57], v[184:187], v[200:203], v[54:57]
	v_mfma_f32_16x16x32_bf16 v[50:53], v[192:195], v[200:203], v[50:53]
	v_mfma_f32_16x16x32_bf16 v[38:41], v[184:187], v[208:211], v[38:41]
	v_mfma_f32_16x16x32_bf16 v[34:37], v[192:195], v[208:211], v[34:37]
	v_mfma_f32_16x16x32_bf16 v[22:25], v[184:187], v[216:219], v[22:25]
	v_mfma_f32_16x16x32_bf16 v[18:21], v[192:195], v[216:219], v[18:21]
	v_mfma_f32_16x16x32_bf16 v[6:9], v[184:187], v[228:231], v[6:9]
	v_mfma_f32_16x16x32_bf16 v[2:5], v[192:195], v[228:231], v[2:5]
	s_barrier
; #define PG8_STAGE(bufoff, gbase, voff) do { _Pragma("unroll") for (int _i = 0; _i < 2; ++_i) \
;         __builtin_amdgcn_global_load_lds((const unsigned*)((const char*)(gbase) + (voff)[_i]), (PG8_LAS unsigned*)(lds + (bufoff) + ldsw + _i * 8192), 16, 0, 0); } while (0)
; #define PG8_LDA(dst, b, h) do { _Pragma("unroll") for (int m = 0; m < 4; ++m) _Pragma("unroll") for (int k = 0; k < 2; ++k) dst[m][k] = *(const PG8_LAS bf16x8*)(lds + PG8_SA(b, h) + aoff + m * 2048 + k * 1024); } while (0)
; #define PG8_LDB(dst, b, h) do { _Pragma("unroll") for (int n = 0; n < 2; ++n) _Pragma("unroll") for (int k = 0; k < 2; ++k) dst[n][k] = *(const PG8_LAS bf16x8*)(lds + PG8_SB(b, h) + boff + n * 2048 + k * 1024); } while (0)
; #define PG8_MMA(ai, bj, At, Bt) do { __builtin_amdgcn_s_setprio(1); _Pragma("unroll") for (int m = 0; m < 4; ++m) _Pragma("unroll") for (int n = 0; n < 2; ++n) _Pragma("unroll") for (int k = 0; k < 2; ++k) \
;         acc[ai][bj][m][n] = __builtin_amdgcn_mfma_f32_16x16x32_bf16(Bt[n][k], At[m][k], acc[ai][bj][m][n], 0, 0, 0); __builtin_amdgcn_s_setprio(0); } while (0)
; #define PG8_WAIT_V(n) asm volatile("s_waitcnt vmcnt(" #n ")" ::: "memory")
; #define PG8_WAIT_L(n) asm volatile("s_waitcnt lgkmcnt(" #n ")" ::: "memory")
; #define PG8_BAR __builtin_amdgcn_s_barrier()
; #define PG8_SCHED __builtin_amdgcn_sched_barrier(0)
; template <class Epi, class Sched, bool ALIGN_EPI = false, bool SP2 = false>
; __device__ __forceinline__ void gemm_phase(PG8_LAS unsigned char* lds, const Gemm g, const Sched& S, const Epi& E) {
;     ...
;             PG8_LDB(B0, 1, 0); PG8_LDB(B1, 1, 1); PG8_SCHED; PG8_LDA(At, 1, 0); PG8_STAGE(PG8_SA(0, 1), a2 + hA, voffA);
;             PG8_WAIT_V(8); PG8_WAIT_L(0); PG8_BAR; PG8_MMA(0, 0, At, B0); PG8_MMA(0, 1, At, B1); PG8_BAR; PG8_SCHED;
;             PG8_LDA(At, 1, 1); PG8_STAGE(PG8_SB(1, 0), b3, voffB); PG8_STAGE(PG8_SB(1, 1), b3 + hB, voffB); PG8_STAGE(PG8_SA(1, 0), a3, voffA);
;             PG8_WAIT_V(8); PG8_WAIT_L(0); PG8_BAR; PG8_MMA(1, 0, At, B0); PG8_MMA(1, 1, At, B1); PG8_BAR; PG8_SCHED;
	s_add_i32 s18, 0, 0x18000
	s_add_i32 s19, 0, 0x1c000
	v_add_u32_e32 v160, s18, v165
	v_add_u32_e32 v164, s19, v165
	ds_read_b128 v[148:151], v160
	ds_read_b128 v[152:155], v160 offset:1024
	ds_read_b128 v[156:159], v160 offset:2048
	ds_read_b128 v[160:163], v160 offset:3072
	ds_read_b128 v[180:183], v164
	ds_read_b128 v[184:187], v164 offset:1024
	ds_read_b128 v[188:191], v164 offset:2048
	ds_read_b128 v[192:195], v164 offset:3072
	s_add_u32 s44, s44, 0x80000
	s_addc_u32 s45, s45, 0
	s_mov_b32 m0, s53
	ds_read_b128 v[196:199], v173 offset:32768
	ds_read_b128 v[200:203], v173 offset:33792
	ds_read_b128 v[204:207], v173 offset:34816
	ds_read_b128 v[208:211], v173 offset:35840
	ds_read_b128 v[212:215], v173 offset:36864
	ds_read_b128 v[216:219], v173 offset:37888
	ds_read_b128 v[224:227], v173 offset:38912
	ds_read_b128 v[228:231], v173 offset:39936
	global_load_lds_dwordx4 v136, s[44:45]
	s_mov_b32 m0, s57
	s_nop 0
	global_load_lds_dwordx4 v132, s[44:45]
	s_waitcnt vmcnt(8)
	s_waitcnt lgkmcnt(0)
	s_barrier
	s_waitcnt lgkmcnt(0)
	v_mfma_f32_16x16x32_bf16 v[126:129], v[148:151], v[196:199], v[126:129]
	v_mfma_f32_16x16x32_bf16 v[122:125], v[156:159], v[196:199], v[122:125]
	v_mfma_f32_16x16x32_bf16 v[110:113], v[148:151], v[204:207], v[110:113]
	v_mfma_f32_16x16x32_bf16 v[106:109], v[156:159], v[204:207], v[106:109]
	v_mfma_f32_16x16x32_bf16 v[94:97], v[148:151], v[212:215], v[94:97]
	v_mfma_f32_16x16x32_bf16 v[90:93], v[156:159], v[212:215], v[90:93]
	v_mfma_f32_16x16x32_bf16 v[78:81], v[148:151], v[224:227], v[78:81]
	v_mfma_f32_16x16x32_bf16 v[74:77], v[156:159], v[224:227], v[74:77]
	v_mfma_f32_16x16x32_bf16 v[126:129], v[152:155], v[200:203], v[126:129]
	v_mfma_f32_16x16x32_bf16 v[122:125], v[160:163], v[200:203], v[122:125]
	v_mfma_f32_16x16x32_bf16 v[110:113], v[152:155], v[208:211], v[110:113]
	v_mfma_f32_16x16x32_bf16 v[106:109], v[160:163], v[208:211], v[106:109]
	v_mfma_f32_16x16x32_bf16 v[94:97], v[152:155], v[216:219], v[94:97]
	v_mfma_f32_16x16x32_bf16 v[90:93], v[160:163], v[216:219], v[90:93]
	v_mfma_f32_16x16x32_bf16 v[78:81], v[152:155], v[228:231], v[78:81]
	v_mfma_f32_16x16x32_bf16 v[74:77], v[160:163], v[228:231], v[74:77]
	v_mfma_f32_16x16x32_bf16 v[118:121], v[180:183], v[196:199], v[118:121]
	v_mfma_f32_16x16x32_bf16 v[114:117], v[188:191], v[196:199], v[114:117]
	v_mfma_f32_16x16x32_bf16 v[102:105], v[180:183], v[204:207], v[102:105]
	v_mfma_f32_16x16x32_bf16 v[98:101], v[188:191], v[204:207], v[98:101]
	v_mfma_f32_16x16x32_bf16 v[86:89], v[180:183], v[212:215], v[86:89]
	v_mfma_f32_16x16x32_bf16 v[82:85], v[188:191], v[212:215], v[82:85]
	v_mfma_f32_16x16x32_bf16 v[70:73], v[180:183], v[224:227], v[70:73]
	v_mfma_f32_16x16x32_bf16 v[66:69], v[188:191], v[224:227], v[66:69]
	v_mfma_f32_16x16x32_bf16 v[118:121], v[184:187], v[200:203], v[118:121]
	v_mfma_f32_16x16x32_bf16 v[114:117], v[192:195], v[200:203], v[114:117]
	v_mfma_f32_16x16x32_bf16 v[102:105], v[184:187], v[208:211], v[102:105]
	v_mfma_f32_16x16x32_bf16 v[98:101], v[192:195], v[208:211], v[98:101]
	v_mfma_f32_16x16x32_bf16 v[86:89], v[184:187], v[216:219], v[86:89]
	v_mfma_f32_16x16x32_bf16 v[82:85], v[192:195], v[216:219], v[82:85]
	v_mfma_f32_16x16x32_bf16 v[70:73], v[184:187], v[228:231], v[70:73]
	v_mfma_f32_16x16x32_bf16 v[66:69], v[192:195], v[228:231], v[66:69]
	s_barrier
	s_add_i32 s18, s18, s49
	s_mov_b32 m0, s18
	ds_read_b128 v[196:199], v173 offset:49152
	ds_read_b128 v[200:203], v173 offset:50176
	ds_read_b128 v[204:207], v173 offset:51200
	ds_read_b128 v[208:211], v173 offset:52224
	ds_read_b128 v[212:215], v173 offset:53248
	ds_read_b128 v[216:219], v173 offset:54272
	ds_read_b128 v[224:227], v173 offset:55296
	ds_read_b128 v[228:231], v173 offset:56320
	global_load_lds_dwordx4 v134, s[76:77]
	s_add_i32 m0, s18, 0x2000
	s_add_u32 s42, s42, 0x80080
	s_addc_u32 s43, s43, 0
	s_add_i32 s18, s19, s49
	global_load_lds_dwordx4 v130, s[76:77]
	s_mov_b32 m0, s18
	s_nop 0
	global_load_lds_dwordx4 v134, s[42:43]
	s_add_i32 m0, s18, 0x2000
	s_nop 0
	global_load_lds_dwordx4 v130, s[42:43]
	s_mov_b32 m0, s60
	s_nop 0
	global_load_lds_dwordx4 v136, s[78:79]
	s_mov_b32 m0, s61
	s_nop 0
	global_load_lds_dwordx4 v132, s[78:79]
	s_waitcnt vmcnt(8)
	s_waitcnt lgkmcnt(0)
	s_barrier
	s_waitcnt lgkmcnt(0)
	v_mfma_f32_16x16x32_bf16 v[62:65], v[148:151], v[196:199], v[62:65]
	v_mfma_f32_16x16x32_bf16 v[58:61], v[156:159], v[196:199], v[58:61]
	v_mfma_f32_16x16x32_bf16 v[46:49], v[148:151], v[204:207], v[46:49]
	v_mfma_f32_16x16x32_bf16 v[42:45], v[156:159], v[204:207], v[42:45]
	v_mfma_f32_16x16x32_bf16 v[30:33], v[148:151], v[212:215], v[30:33]
	v_mfma_f32_16x16x32_bf16 v[26:29], v[156:159], v[212:215], v[26:29]
	v_mfma_f32_16x16x32_bf16 v[14:17], v[148:151], v[224:227], v[14:17]
	v_mfma_f32_16x16x32_bf16 v[10:13], v[156:159], v[224:227], v[10:13]
	v_mfma_f32_16x16x32_bf16 v[62:65], v[152:155], v[200:203], v[62:65]
	v_mfma_f32_16x16x32_bf16 v[58:61], v[160:163], v[200:203], v[58:61]
	v_mfma_f32_16x16x32_bf16 v[46:49], v[152:155], v[208:211], v[46:49]
	v_mfma_f32_16x16x32_bf16 v[42:45], v[160:163], v[208:211], v[42:45]
	v_mfma_f32_16x16x32_bf16 v[30:33], v[152:155], v[216:219], v[30:33]
	v_mfma_f32_16x16x32_bf16 v[26:29], v[160:163], v[216:219], v[26:29]
	v_mfma_f32_16x16x32_bf16 v[14:17], v[152:155], v[228:231], v[14:17]
	v_mfma_f32_16x16x32_bf16 v[10:13], v[160:163], v[228:231], v[10:13]
	v_mfma_f32_16x16x32_bf16 v[54:57], v[180:183], v[196:199], v[54:57]
	v_mfma_f32_16x16x32_bf16 v[50:53], v[188:191], v[196:199], v[50:53]
	v_mfma_f32_16x16x32_bf16 v[38:41], v[180:183], v[204:207], v[38:41]
	v_mfma_f32_16x16x32_bf16 v[34:37], v[188:191], v[204:207], v[34:37]
	v_mfma_f32_16x16x32_bf16 v[22:25], v[180:183], v[212:215], v[22:25]
	v_mfma_f32_16x16x32_bf16 v[18:21], v[188:191], v[212:215], v[18:21]
	v_mfma_f32_16x16x32_bf16 v[6:9], v[180:183], v[224:227], v[6:9]
	v_mfma_f32_16x16x32_bf16 v[2:5], v[188:191], v[224:227], v[2:5]
	v_mfma_f32_16x16x32_bf16 v[54:57], v[184:187], v[200:203], v[54:57]
	v_mfma_f32_16x16x32_bf16 v[50:53], v[192:195], v[200:203], v[50:53]
	v_mfma_f32_16x16x32_bf16 v[38:41], v[184:187], v[208:211], v[38:41]
	v_mfma_f32_16x16x32_bf16 v[34:37], v[192:195], v[208:211], v[34:37]
	v_mfma_f32_16x16x32_bf16 v[22:25], v[184:187], v[216:219], v[22:25]
	v_mfma_f32_16x16x32_bf16 v[18:21], v[192:195], v[216:219], v[18:21]
	v_mfma_f32_16x16x32_bf16 v[6:9], v[184:187], v[228:231], v[6:9]
	v_mfma_f32_16x16x32_bf16 v[2:5], v[192:195], v[228:231], v[2:5]
	s_barrier
	s_add_i32 s72, s72, 2
	s_add_u32 s8, s8, 0x100
	s_addc_u32 s9, s9, 0
	s_add_u32 s70, s70, 0x100
	s_addc_u32 s71, s71, 0
	s_cmp_gt_u32 s72, 29
	s_cbranch_scc0 .LBB0_1048
	s_and_b64 vcc, exec, s[22:23]
	s_cbranch_vccz .LBB0_1051
	s_barrier

; #define PG8_STAGE(bufoff, gbase, voff) do { _Pragma("unroll") for (int _i = 0; _i < 2; ++_i) \
;         __builtin_amdgcn_global_load_lds((const unsigned*)((const char*)(gbase) + (voff)[_i]), (PG8_LAS unsigned*)(lds + (bufoff) + ldsw + _i * 8192), 16, 0, 0); } while (0)
; #define PG8_LDA(dst, b, h) do { _Pragma("unroll") for (int m = 0; m < 4; ++m) _Pragma("unroll") for (int k = 0; k < 2; ++k) dst[m][k] = *(const PG8_LAS bf16x8*)(lds + PG8_SA(b, h) + aoff + m * 2048 + k * 1024); } while (0)
; #define PG8_LDB(dst, b, h) do { _Pragma("unroll") for (int n = 0; n < 2; ++n) _Pragma("unroll") for (int k = 0; k < 2; ++k) dst[n][k] = *(const PG8_LAS bf16x8*)(lds + PG8_SB(b, h) + boff + n * 2048 + k * 1024); } while (0)
; #define PG8_MMA(ai, bj, At, Bt) do { __builtin_amdgcn_s_setprio(1); _Pragma("unroll") for (int m = 0; m < 4; ++m) _Pragma("unroll") for (int n = 0; n < 2; ++n) _Pragma("unroll") for (int k = 0; k < 2; ++k) \
;         acc[ai][bj][m][n] = __builtin_amdgcn_mfma_f32_16x16x32_bf16(Bt[n][k], At[m][k], acc[ai][bj][m][n], 0, 0, 0); __builtin_amdgcn_s_setprio(0); } while (0)
; #define PG8_WAIT_V(n) asm volatile("s_waitcnt vmcnt(" #n ")" ::: "memory")
; #define PG8_WAIT_L(n) asm volatile("s_waitcnt lgkmcnt(" #n ")" ::: "memory")
; #define PG8_BAR __builtin_amdgcn_s_barrier()
; #define PG8_SCHED __builtin_amdgcn_sched_barrier(0)
; template <class Epi, class Sched, bool ALIGN_EPI = false, bool SP2 = false>
; __device__ __forceinline__ void gemm_phase(PG8_LAS unsigned char* lds, const Gemm g, const Sched& S, const Epi& E) {
;     ...
;             PG8_LDB(B0, 0, 0); PG8_LDB(B1, 0, 1); PG8_SCHED; PG8_LDA(At, 0, 0); PG8_STAGE(PG8_SA(1, 1), a1 + hA, voffA);
;             PG8_WAIT_V(8); PG8_WAIT_L(0); PG8_BAR; PG8_MMA(0, 0, At, B0); PG8_MMA(0, 1, At, B1); PG8_BAR; PG8_SCHED;
;             PG8_LDA(At, 0, 1); PG8_STAGE(PG8_SB(0, 0), b2, voffB); PG8_STAGE(PG8_SB(0, 1), b2 + hB, voffB); PG8_STAGE(PG8_SA(0, 0), a2, voffA);
;             PG8_WAIT_V(8); PG8_WAIT_L(0); PG8_BAR; PG8_MMA(1, 0, At, B0); PG8_MMA(1, 1, At, B1); PG8_BAR; PG8_SCHED;
.LBB0_1127:
	ds_read_b128 v[130:133], v190
	ds_read_b128 v[134:137], v190 offset:1024
	ds_read_b128 v[138:141], v190 offset:2048
	ds_read_b128 v[142:145], v190 offset:3072
	ds_read_b128 v[146:149], v191
	ds_read_b128 v[150:153], v191 offset:1024
	ds_read_b128 v[170:173], v191 offset:2048
	ds_read_b128 v[174:177], v191 offset:3072
	s_add_u32 s36, s24, 0x100
	s_addc_u32 s37, s25, 0
	s_cmpk_eq_i32 s63, 0x54
	s_cselect_b32 s41, s9, s37
	s_cselect_b32 s40, s8, s36
	s_cselect_b32 s39, s23, s62
	s_cselect_b32 s38, s22, s61
	s_add_i32 m0, s46, 0xc000
	ds_read_b128 v[178:181], v192
	ds_read_b128 v[182:185], v192 offset:1024
	ds_read_b128 v[194:197], v192 offset:2048
	ds_read_b128 v[198:201], v192 offset:3072
	ds_read_b128 v[202:205], v192 offset:4096
	ds_read_b128 v[206:209], v192 offset:5120
	ds_read_b128 v[210:213], v192 offset:6144
	ds_read_b128 v[214:217], v192 offset:7168
	global_load_lds_dwordx4 v162, s[24:25]
	s_add_i32 m0, s46, 0xe000
	s_nop 0
	global_load_lds_dwordx4 v164, s[24:25]
	s_waitcnt vmcnt(8)
	s_waitcnt lgkmcnt(0)
	s_barrier
	s_waitcnt lgkmcnt(0)
	v_mfma_f32_16x16x32_bf16 v[126:129], v[130:133], v[178:181], v[126:129]
	v_mfma_f32_16x16x32_bf16 v[122:125], v[138:141], v[178:181], v[122:125]
	v_mfma_f32_16x16x32_bf16 v[110:113], v[130:133], v[194:197], v[110:113]
	v_mfma_f32_16x16x32_bf16 v[106:109], v[138:141], v[194:197], v[106:109]
	v_mfma_f32_16x16x32_bf16 v[94:97], v[130:133], v[202:205], v[94:97]
	v_mfma_f32_16x16x32_bf16 v[90:93], v[138:141], v[202:205], v[90:93]
	v_mfma_f32_16x16x32_bf16 v[78:81], v[130:133], v[210:213], v[78:81]
	v_mfma_f32_16x16x32_bf16 v[74:77], v[138:141], v[210:213], v[74:77]
	v_mfma_f32_16x16x32_bf16 v[126:129], v[134:137], v[182:185], v[126:129]
	v_mfma_f32_16x16x32_bf16 v[122:125], v[142:145], v[182:185], v[122:125]
	v_mfma_f32_16x16x32_bf16 v[110:113], v[134:137], v[198:201], v[110:113]
	v_mfma_f32_16x16x32_bf16 v[106:109], v[142:145], v[198:201], v[106:109]
	v_mfma_f32_16x16x32_bf16 v[94:97], v[134:137], v[206:209], v[94:97]
	v_mfma_f32_16x16x32_bf16 v[90:93], v[142:145], v[206:209], v[90:93]
	v_mfma_f32_16x16x32_bf16 v[78:81], v[134:137], v[214:217], v[78:81]
	v_mfma_f32_16x16x32_bf16 v[74:77], v[142:145], v[214:217], v[74:77]
	v_mfma_f32_16x16x32_bf16 v[118:121], v[146:149], v[178:181], v[118:121]
	v_mfma_f32_16x16x32_bf16 v[114:117], v[170:173], v[178:181], v[114:117]
	v_mfma_f32_16x16x32_bf16 v[102:105], v[146:149], v[194:197], v[102:105]
	v_mfma_f32_16x16x32_bf16 v[98:101], v[170:173], v[194:197], v[98:101]
	v_mfma_f32_16x16x32_bf16 v[86:89], v[146:149], v[202:205], v[86:89]
	v_mfma_f32_16x16x32_bf16 v[82:85], v[170:173], v[202:205], v[82:85]
	v_mfma_f32_16x16x32_bf16 v[70:73], v[146:149], v[210:213], v[70:73]
	v_mfma_f32_16x16x32_bf16 v[66:69], v[170:173], v[210:213], v[66:69]
	v_mfma_f32_16x16x32_bf16 v[118:121], v[150:153], v[182:185], v[118:121]
	v_mfma_f32_16x16x32_bf16 v[114:117], v[174:177], v[182:185], v[114:117]
	v_mfma_f32_16x16x32_bf16 v[102:105], v[150:153], v[198:201], v[102:105]
	v_mfma_f32_16x16x32_bf16 v[98:101], v[174:177], v[198:201], v[98:101]
	v_mfma_f32_16x16x32_bf16 v[86:89], v[150:153], v[206:209], v[86:89]
	v_mfma_f32_16x16x32_bf16 v[82:85], v[174:177], v[206:209], v[82:85]
	v_mfma_f32_16x16x32_bf16 v[70:73], v[150:153], v[214:217], v[70:73]
	v_mfma_f32_16x16x32_bf16 v[66:69], v[174:177], v[214:217], v[66:69]
	s_barrier
	s_add_i32 s18, s55, s45
	s_add_u32 s76, s38, s16
	s_addc_u32 s77, s39, s17
	s_mov_b32 m0, s18
	ds_read_b128 v[178:181], v192 offset:16384
	ds_read_b128 v[182:185], v192 offset:17408
	ds_read_b128 v[194:197], v192 offset:18432
	ds_read_b128 v[198:201], v192 offset:19456
	ds_read_b128 v[202:205], v192 offset:20480
	ds_read_b128 v[206:209], v192 offset:21504
	ds_read_b128 v[210:213], v192 offset:22528
	ds_read_b128 v[214:217], v192 offset:23552
	global_load_lds_dwordx4 v156, s[38:39]
	s_add_i32 m0, s18, 0x2000
	s_add_u32 s24, s38, 0x160000
	s_addc_u32 s25, s39, 0
	s_add_i32 s18, s56, s45
	global_load_lds_dwordx4 v160, s[38:39]
	s_mov_b32 m0, s18
	s_nop 0
	global_load_lds_dwordx4 v156, s[24:25]
	s_add_i32 m0, s18, 0x2000
	s_nop 0
	global_load_lds_dwordx4 v160, s[24:25]
	s_add_u32 s78, s40, s16
	s_addc_u32 s79, s41, s17
	s_mov_b32 m0, s46
	s_nop 0
	global_load_lds_dwordx4 v154, s[40:41]
	s_mov_b32 m0, s47
	s_nop 0
	global_load_lds_dwordx4 v158, s[40:41]
	s_waitcnt vmcnt(8)
	s_waitcnt lgkmcnt(0)
	s_barrier
	s_waitcnt lgkmcnt(0)
	v_mfma_f32_16x16x32_bf16 v[62:65], v[130:133], v[178:181], v[62:65]
	v_mfma_f32_16x16x32_bf16 v[58:61], v[138:141], v[178:181], v[58:61]
	v_mfma_f32_16x16x32_bf16 v[46:49], v[130:133], v[194:197], v[46:49]
	v_mfma_f32_16x16x32_bf16 v[42:45], v[138:141], v[194:197], v[42:45]
	v_mfma_f32_16x16x32_bf16 v[30:33], v[130:133], v[202:205], v[30:33]
	v_mfma_f32_16x16x32_bf16 v[26:29], v[138:141], v[202:205], v[26:29]
	v_mfma_f32_16x16x32_bf16 v[14:17], v[130:133], v[210:213], v[14:17]
	v_mfma_f32_16x16x32_bf16 v[10:13], v[138:141], v[210:213], v[10:13]
	v_mfma_f32_16x16x32_bf16 v[62:65], v[134:137], v[182:185], v[62:65]
	v_mfma_f32_16x16x32_bf16 v[58:61], v[142:145], v[182:185], v[58:61]
	v_mfma_f32_16x16x32_bf16 v[46:49], v[134:137], v[198:201], v[46:49]
	v_mfma_f32_16x16x32_bf16 v[42:45], v[142:145], v[198:201], v[42:45]
	v_mfma_f32_16x16x32_bf16 v[30:33], v[134:137], v[206:209], v[30:33]
	v_mfma_f32_16x16x32_bf16 v[26:29], v[142:145], v[206:209], v[26:29]
	v_mfma_f32_16x16x32_bf16 v[14:17], v[134:137], v[214:217], v[14:17]
	v_mfma_f32_16x16x32_bf16 v[10:13], v[142:145], v[214:217], v[10:13]
	v_mfma_f32_16x16x32_bf16 v[54:57], v[146:149], v[178:181], v[54:57]
	v_mfma_f32_16x16x32_bf16 v[50:53], v[170:173], v[178:181], v[50:53]
	v_mfma_f32_16x16x32_bf16 v[38:41], v[146:149], v[194:197], v[38:41]
	v_mfma_f32_16x16x32_bf16 v[34:37], v[170:173], v[194:197], v[34:37]
	v_mfma_f32_16x16x32_bf16 v[22:25], v[146:149], v[202:205], v[22:25]
	v_mfma_f32_16x16x32_bf16 v[18:21], v[170:173], v[202:205], v[18:21]
	v_mfma_f32_16x16x32_bf16 v[6:9], v[146:149], v[210:213], v[6:9]
	v_mfma_f32_16x16x32_bf16 v[2:5], v[170:173], v[210:213], v[2:5]
	v_mfma_f32_16x16x32_bf16 v[54:57], v[150:153], v[182:185], v[54:57]
	v_mfma_f32_16x16x32_bf16 v[50:53], v[174:177], v[182:185], v[50:53]
	v_mfma_f32_16x16x32_bf16 v[38:41], v[150:153], v[198:201], v[38:41]
	v_mfma_f32_16x16x32_bf16 v[34:37], v[174:177], v[198:201], v[34:37]
	v_mfma_f32_16x16x32_bf16 v[22:25], v[150:153], v[206:209], v[22:25]
	v_mfma_f32_16x16x32_bf16 v[18:21], v[174:177], v[206:209], v[18:21]
	v_mfma_f32_16x16x32_bf16 v[6:9], v[150:153], v[214:217], v[6:9]
	v_mfma_f32_16x16x32_bf16 v[2:5], v[174:177], v[214:217], v[2:5]
	s_barrier
; #define PG8_STAGE(bufoff, gbase, voff) do { _Pragma("unroll") for (int _i = 0; _i < 2; ++_i) \
;         __builtin_amdgcn_global_load_lds((const unsigned*)((const char*)(gbase) + (voff)[_i]), (PG8_LAS unsigned*)(lds + (bufoff) + ldsw + _i * 8192), 16, 0, 0); } while (0)
; #define PG8_LDA(dst, b, h) do { _Pragma("unroll") for (int m = 0; m < 4; ++m) _Pragma("unroll") for (int k = 0; k < 2; ++k) dst[m][k] = *(const PG8_LAS bf16x8*)(lds + PG8_SA(b, h) + aoff + m * 2048 + k * 1024); } while (0)
; #define PG8_LDB(dst, b, h) do { _Pragma("unroll") for (int n = 0; n < 2; ++n) _Pragma("unroll") for (int k = 0; k < 2; ++k) dst[n][k] = *(const PG8_LAS bf16x8*)(lds + PG8_SB(b, h) + boff + n * 2048 + k * 1024); } while (0)
; #define PG8_MMA(ai, bj, At, Bt) do { __builtin_amdgcn_s_setprio(1); _Pragma("unroll") for (int m = 0; m < 4; ++m) _Pragma("unroll") for (int n = 0; n < 2; ++n) _Pragma("unroll") for (int k = 0; k < 2; ++k) \
;         acc[ai][bj][m][n] = __builtin_amdgcn_mfma_f32_16x16x32_bf16(Bt[n][k], At[m][k], acc[ai][bj][m][n], 0, 0, 0); __builtin_amdgcn_s_setprio(0); } while (0)
; #define PG8_WAIT_V(n) asm volatile("s_waitcnt vmcnt(" #n ")" ::: "memory")
; #define PG8_WAIT_L(n) asm volatile("s_waitcnt lgkmcnt(" #n ")" ::: "memory")
; #define PG8_BAR __builtin_amdgcn_s_barrier()
; #define PG8_SCHED __builtin_amdgcn_sched_barrier(0)
; template <class Epi, class Sched, bool ALIGN_EPI = false, bool SP2 = false>
; __device__ __forceinline__ void gemm_phase(PG8_LAS unsigned char* lds, const Gemm g, const Sched& S, const Epi& E) {
;     ...
;             PG8_LDB(B0, 1, 0); PG8_LDB(B1, 1, 1); PG8_SCHED; PG8_LDA(At, 1, 0); PG8_STAGE(PG8_SA(0, 1), a2 + hA, voffA);
;             PG8_WAIT_V(8); PG8_WAIT_L(0); PG8_BAR; PG8_MMA(0, 0, At, B0); PG8_MMA(0, 1, At, B1); PG8_BAR; PG8_SCHED;
;             PG8_LDA(At, 1, 1); PG8_STAGE(PG8_SB(1, 0), b3, voffB); PG8_STAGE(PG8_SB(1, 1), b3 + hB, voffB); PG8_STAGE(PG8_SA(1, 0), a3, voffA);
;             PG8_WAIT_V(8); PG8_WAIT_L(0); PG8_BAR; PG8_MMA(1, 0, At, B0); PG8_MMA(1, 1, At, B1); PG8_BAR; PG8_SCHED;
	s_add_i32 s18, 0, 0x18000
	s_add_i32 s19, 0, 0x1c000
	v_add_u32_e32 v142, s18, v188
	v_add_u32_e32 v174, s19, v188
	ds_read_b128 v[130:133], v142
	ds_read_b128 v[134:137], v142 offset:1024
	ds_read_b128 v[138:141], v142 offset:2048
	ds_read_b128 v[142:145], v142 offset:3072
	ds_read_b128 v[146:149], v174
	ds_read_b128 v[150:153], v174 offset:1024
	ds_read_b128 v[170:173], v174 offset:2048
	ds_read_b128 v[174:177], v174 offset:3072
	s_add_u32 s24, s40, 0x160000
	s_addc_u32 s25, s41, 0
	s_mov_b32 m0, s48
	ds_read_b128 v[178:181], v192 offset:32768
	ds_read_b128 v[182:185], v192 offset:33792
	ds_read_b128 v[194:197], v192 offset:34816
	ds_read_b128 v[198:201], v192 offset:35840
	ds_read_b128 v[202:205], v192 offset:36864
	ds_read_b128 v[206:209], v192 offset:37888
	ds_read_b128 v[210:213], v192 offset:38912
	ds_read_b128 v[214:217], v192 offset:39936
	global_load_lds_dwordx4 v154, s[24:25]
	s_mov_b32 m0, s49
	s_nop 0
	global_load_lds_dwordx4 v158, s[24:25]
	s_waitcnt vmcnt(8)
	s_waitcnt lgkmcnt(0)
	s_barrier
	s_waitcnt lgkmcnt(0)
	v_mfma_f32_16x16x32_bf16 v[126:129], v[130:133], v[178:181], v[126:129]
	v_mfma_f32_16x16x32_bf16 v[122:125], v[138:141], v[178:181], v[122:125]
	v_mfma_f32_16x16x32_bf16 v[110:113], v[130:133], v[194:197], v[110:113]
	v_mfma_f32_16x16x32_bf16 v[106:109], v[138:141], v[194:197], v[106:109]
	v_mfma_f32_16x16x32_bf16 v[94:97], v[130:133], v[202:205], v[94:97]
	v_mfma_f32_16x16x32_bf16 v[90:93], v[138:141], v[202:205], v[90:93]
	v_mfma_f32_16x16x32_bf16 v[78:81], v[130:133], v[210:213], v[78:81]
	v_mfma_f32_16x16x32_bf16 v[74:77], v[138:141], v[210:213], v[74:77]
	v_mfma_f32_16x16x32_bf16 v[126:129], v[134:137], v[182:185], v[126:129]
	v_mfma_f32_16x16x32_bf16 v[122:125], v[142:145], v[182:185], v[122:125]
	v_mfma_f32_16x16x32_bf16 v[110:113], v[134:137], v[198:201], v[110:113]
	v_mfma_f32_16x16x32_bf16 v[106:109], v[142:145], v[198:201], v[106:109]
	v_mfma_f32_16x16x32_bf16 v[94:97], v[134:137], v[206:209], v[94:97]
	v_mfma_f32_16x16x32_bf16 v[90:93], v[142:145], v[206:209], v[90:93]
	v_mfma_f32_16x16x32_bf16 v[78:81], v[134:137], v[214:217], v[78:81]
	v_mfma_f32_16x16x32_bf16 v[74:77], v[142:145], v[214:217], v[74:77]
	v_mfma_f32_16x16x32_bf16 v[118:121], v[146:149], v[178:181], v[118:121]
	v_mfma_f32_16x16x32_bf16 v[114:117], v[170:173], v[178:181], v[114:117]
	v_mfma_f32_16x16x32_bf16 v[102:105], v[146:149], v[194:197], v[102:105]
	v_mfma_f32_16x16x32_bf16 v[98:101], v[170:173], v[194:197], v[98:101]
	v_mfma_f32_16x16x32_bf16 v[86:89], v[146:149], v[202:205], v[86:89]
	v_mfma_f32_16x16x32_bf16 v[82:85], v[170:173], v[202:205], v[82:85]
	v_mfma_f32_16x16x32_bf16 v[70:73], v[146:149], v[210:213], v[70:73]
	v_mfma_f32_16x16x32_bf16 v[66:69], v[170:173], v[210:213], v[66:69]
	v_mfma_f32_16x16x32_bf16 v[118:121], v[150:153], v[182:185], v[118:121]
	v_mfma_f32_16x16x32_bf16 v[114:117], v[174:177], v[182:185], v[114:117]
	v_mfma_f32_16x16x32_bf16 v[102:105], v[150:153], v[198:201], v[102:105]
	v_mfma_f32_16x16x32_bf16 v[98:101], v[174:177], v[198:201], v[98:101]
	v_mfma_f32_16x16x32_bf16 v[86:89], v[150:153], v[206:209], v[86:89]
	v_mfma_f32_16x16x32_bf16 v[82:85], v[174:177], v[206:209], v[82:85]
	v_mfma_f32_16x16x32_bf16 v[70:73], v[150:153], v[214:217], v[70:73]
	v_mfma_f32_16x16x32_bf16 v[66:69], v[174:177], v[214:217], v[66:69]
	s_barrier
	s_add_i32 s18, s18, s45
	s_mov_b32 m0, s18
	ds_read_b128 v[178:181], v192 offset:49152
	ds_read_b128 v[182:185], v192 offset:50176
	ds_read_b128 v[194:197], v192 offset:51200
	ds_read_b128 v[198:201], v192 offset:52224
	ds_read_b128 v[202:205], v192 offset:53248
	ds_read_b128 v[206:209], v192 offset:54272
	ds_read_b128 v[210:213], v192 offset:55296
	ds_read_b128 v[214:217], v192 offset:56320
	global_load_lds_dwordx4 v156, s[76:77]
	s_add_i32 m0, s18, 0x2000
	s_add_u32 s24, s38, 0x160080
	s_addc_u32 s25, s39, 0
	s_add_i32 s18, s19, s45
	global_load_lds_dwordx4 v160, s[76:77]
	s_mov_b32 m0, s18
	s_nop 0
	global_load_lds_dwordx4 v156, s[24:25]
	s_add_i32 m0, s18, 0x2000
	s_nop 0
	global_load_lds_dwordx4 v160, s[24:25]
	s_mov_b32 m0, s52
	s_nop 0
	global_load_lds_dwordx4 v154, s[78:79]
	s_mov_b32 m0, s53
	s_nop 0
	global_load_lds_dwordx4 v158, s[78:79]
	s_waitcnt vmcnt(8)
	s_waitcnt lgkmcnt(0)
	s_barrier
	s_waitcnt lgkmcnt(0)
	v_mfma_f32_16x16x32_bf16 v[62:65], v[130:133], v[178:181], v[62:65]
	v_mfma_f32_16x16x32_bf16 v[58:61], v[138:141], v[178:181], v[58:61]
	v_mfma_f32_16x16x32_bf16 v[46:49], v[130:133], v[194:197], v[46:49]
	v_mfma_f32_16x16x32_bf16 v[42:45], v[138:141], v[194:197], v[42:45]
	v_mfma_f32_16x16x32_bf16 v[30:33], v[130:133], v[202:205], v[30:33]
	v_mfma_f32_16x16x32_bf16 v[26:29], v[138:141], v[202:205], v[26:29]
	v_mfma_f32_16x16x32_bf16 v[14:17], v[130:133], v[210:213], v[14:17]
	v_mfma_f32_16x16x32_bf16 v[10:13], v[138:141], v[210:213], v[10:13]
	v_mfma_f32_16x16x32_bf16 v[62:65], v[134:137], v[182:185], v[62:65]
	v_mfma_f32_16x16x32_bf16 v[58:61], v[142:145], v[182:185], v[58:61]
	v_mfma_f32_16x16x32_bf16 v[46:49], v[134:137], v[198:201], v[46:49]
	v_mfma_f32_16x16x32_bf16 v[42:45], v[142:145], v[198:201], v[42:45]
	v_mfma_f32_16x16x32_bf16 v[30:33], v[134:137], v[206:209], v[30:33]
	v_mfma_f32_16x16x32_bf16 v[26:29], v[142:145], v[206:209], v[26:29]
	v_mfma_f32_16x16x32_bf16 v[14:17], v[134:137], v[214:217], v[14:17]
	v_mfma_f32_16x16x32_bf16 v[10:13], v[142:145], v[214:217], v[10:13]
	v_mfma_f32_16x16x32_bf16 v[54:57], v[146:149], v[178:181], v[54:57]
	v_mfma_f32_16x16x32_bf16 v[50:53], v[170:173], v[178:181], v[50:53]
	v_mfma_f32_16x16x32_bf16 v[38:41], v[146:149], v[194:197], v[38:41]
	v_mfma_f32_16x16x32_bf16 v[34:37], v[170:173], v[194:197], v[34:37]
	v_mfma_f32_16x16x32_bf16 v[22:25], v[146:149], v[202:205], v[22:25]
	v_mfma_f32_16x16x32_bf16 v[18:21], v[170:173], v[202:205], v[18:21]
	v_mfma_f32_16x16x32_bf16 v[6:9], v[146:149], v[210:213], v[6:9]
	v_mfma_f32_16x16x32_bf16 v[2:5], v[170:173], v[210:213], v[2:5]
	v_mfma_f32_16x16x32_bf16 v[54:57], v[150:153], v[182:185], v[54:57]
	v_mfma_f32_16x16x32_bf16 v[50:53], v[174:177], v[182:185], v[50:53]
	v_mfma_f32_16x16x32_bf16 v[38:41], v[150:153], v[198:201], v[38:41]
	v_mfma_f32_16x16x32_bf16 v[34:37], v[174:177], v[198:201], v[34:37]
	v_mfma_f32_16x16x32_bf16 v[22:25], v[150:153], v[206:209], v[22:25]
	v_mfma_f32_16x16x32_bf16 v[18:21], v[174:177], v[206:209], v[18:21]
	v_mfma_f32_16x16x32_bf16 v[6:9], v[150:153], v[214:217], v[6:9]
	v_mfma_f32_16x16x32_bf16 v[2:5], v[174:177], v[214:217], v[2:5]
	s_barrier
	s_add_i32 s63, s63, 2
	s_add_u32 s61, s61, 0x100
	s_addc_u32 s62, s62, 0
	s_cmpk_gt_u32 s63, 0x55
	s_mov_b64 s[24:25], s[36:37]
	s_cbranch_scc0 .LBB0_1127
	s_and_b64 vcc, exec, s[20:21]
	s_cbranch_vccz .LBB0_1130
	s_barrier

; __global__ void __launch_bounds__(512, 2) fwd_megakernel(Args a) {
amdhsa.kernels:
  - .agpr_count:     0
    .args:
      - .offset:         0
        .size:           112
        .value_kind:     by_value
      - .offset:         112
        .size:           4
        .value_kind:     hidden_block_count_x
      - .offset:         116
        .size:           4
        .value_kind:     hidden_block_count_y
      - .offset:         120
        .size:           4
        .value_kind:     hidden_block_count_z
      - .offset:         124
        .size:           2
        .value_kind:     hidden_group_size_x
      - .offset:         126
        .size:           2
        .value_kind:     hidden_group_size_y
      - .offset:         128
        .size:           2
        .value_kind:     hidden_group_size_z
      - .offset:         130
        .size:           2
        .value_kind:     hidden_remainder_x
      - .offset:         132
        .size:           2
        .value_kind:     hidden_remainder_y
      - .offset:         134
        .size:           2
        .value_kind:     hidden_remainder_z
      - .offset:         152
        .size:           8
        .value_kind:     hidden_global_offset_x
      - .offset:         160
        .size:           8
        .value_kind:     hidden_global_offset_y
      - .offset:         168
        .size:           8
        .value_kind:     hidden_global_offset_z
      - .offset:         176
        .size:           2
        .value_kind:     hidden_grid_dims
      - .offset:         232
        .size:           4
        .value_kind:     hidden_dynamic_lds_size
    .group_segment_fixed_size: 0
    .kernarg_segment_align: 8
    .kernarg_segment_size: 368
    .language:       OpenCL C
    .language_version:
      - 2
      - 0
    .max_flat_workgroup_size: 512
    .name:           _Z14fwd_megakernel4Args
    .private_segment_fixed_size: 0
    .sgpr_count:     106
    .sgpr_spill_count: 5
    .symbol:         _Z14fwd_megakernel4Args.kd
    .uniform_work_group_size: 1
    .uses_dynamic_stack: false
    .vgpr_count:     256
    .vgpr_spill_count: 0
    .wavefront_size: 64
